# GEMM K-loops: wave priority raised to 2 while a load segment issues its LDS-DMA burst
# baseline (speedup 1.0000x reference)
.LBB0_43:
	s_add_u32 s22, s20, 0xfffc0080
	s_addc_u32 s23, s21, -1
	s_add_i32 s55, 0, 0x10000
	s_cmp_eq_u32 s49, 12
	s_cselect_b32 s25, s13, s23
	s_cselect_b32 s24, s45, s22
	v_add_u32_e32 v148, s55, v162
	s_cselect_b32 s23, s11, s48
	s_cselect_b32 s22, s46, s47
	s_add_i32 s58, 0, 0x14000
	ds_read_b128 v[140:143], v148
	ds_read_b128 v[144:147], v148 offset:1024
	ds_read_b128 v[154:157], v148 offset:2048
	ds_read_b128 v[166:169], v148 offset:3072
	v_add_u32_e32 v148, s58, v162
	ds_read_b128 v[170:173], v148
	ds_read_b128 v[174:177], v148 offset:1024
	ds_read_b128 v[178:181], v148 offset:2048
	ds_read_b128 v[182:185], v148 offset:3072
	v_lshl_add_u64 v[148:149], s[20:21], 0, v[138:139]
	s_add_i32 m0, s19, 0xc000
	ds_read_b128 v[186:189], v164
	ds_read_b128 v[190:193], v164 offset:1024
	ds_read_b128 v[194:197], v164 offset:2048
	ds_read_b128 v[198:201], v164 offset:3072
	ds_read_b128 v[202:205], v164 offset:4096
	ds_read_b128 v[206:209], v164 offset:5120
	ds_read_b128 v[210:213], v164 offset:6144
	ds_read_b128 v[222:225], v164 offset:7168
	s_setprio 2
	global_load_lds_dwordx4 v[148:149], off
	v_lshl_add_u64 v[148:149], s[20:21], 0, v[136:137]
	s_add_i32 m0, s19, 0xe000
	s_nop 0
	global_load_lds_dwordx4 v[148:149], off
	s_setprio 0
	s_cmp_lg_u32 s98, 0
	s_cbranch_scc1 .Lrelax_ff1_w1
	s_waitcnt vmcnt(8)
.Lback_ff1_w1:
	s_waitcnt lgkmcnt(0)
	s_barrier
	s_setprio 1
	s_waitcnt lgkmcnt(0)
	v_mfma_f32_16x16x32_bf16 v[126:129], v[140:143], v[186:189], v[126:129]
	v_mfma_f32_16x16x32_bf16 v[122:125], v[154:157], v[186:189], v[122:125]
	v_mfma_f32_16x16x32_bf16 v[110:113], v[140:143], v[194:197], v[110:113]
	v_mfma_f32_16x16x32_bf16 v[106:109], v[154:157], v[194:197], v[106:109]
	v_mfma_f32_16x16x32_bf16 v[94:97], v[140:143], v[202:205], v[94:97]
	v_mfma_f32_16x16x32_bf16 v[90:93], v[154:157], v[202:205], v[90:93]
	v_mfma_f32_16x16x32_bf16 v[78:81], v[140:143], v[210:213], v[78:81]
	v_mfma_f32_16x16x32_bf16 v[74:77], v[154:157], v[210:213], v[74:77]
	v_mfma_f32_16x16x32_bf16 v[126:129], v[144:147], v[190:193], v[126:129]
	v_mfma_f32_16x16x32_bf16 v[122:125], v[166:169], v[190:193], v[122:125]
	v_mfma_f32_16x16x32_bf16 v[110:113], v[144:147], v[198:201], v[110:113]
	v_mfma_f32_16x16x32_bf16 v[106:109], v[166:169], v[198:201], v[106:109]
	v_mfma_f32_16x16x32_bf16 v[94:97], v[144:147], v[206:209], v[94:97]
	v_mfma_f32_16x16x32_bf16 v[90:93], v[166:169], v[206:209], v[90:93]
	v_mfma_f32_16x16x32_bf16 v[78:81], v[144:147], v[222:225], v[78:81]
	v_mfma_f32_16x16x32_bf16 v[74:77], v[166:169], v[222:225], v[74:77]
	s_setprio 0
	s_setprio 1
	v_mfma_f32_16x16x32_bf16 v[118:121], v[170:173], v[186:189], v[118:121]
	v_mfma_f32_16x16x32_bf16 v[114:117], v[178:181], v[186:189], v[114:117]
	v_mfma_f32_16x16x32_bf16 v[102:105], v[170:173], v[194:197], v[102:105]
	v_mfma_f32_16x16x32_bf16 v[98:101], v[178:181], v[194:197], v[98:101]
	v_mfma_f32_16x16x32_bf16 v[86:89], v[170:173], v[202:205], v[86:89]
	v_mfma_f32_16x16x32_bf16 v[82:85], v[178:181], v[202:205], v[82:85]
	v_mfma_f32_16x16x32_bf16 v[70:73], v[170:173], v[210:213], v[70:73]
	v_mfma_f32_16x16x32_bf16 v[66:69], v[178:181], v[210:213], v[66:69]
	v_mfma_f32_16x16x32_bf16 v[118:121], v[174:177], v[190:193], v[118:121]
	v_mfma_f32_16x16x32_bf16 v[114:117], v[182:185], v[190:193], v[114:117]
	v_mfma_f32_16x16x32_bf16 v[102:105], v[174:177], v[198:201], v[102:105]
	v_mfma_f32_16x16x32_bf16 v[98:101], v[182:185], v[198:201], v[98:101]
	v_mfma_f32_16x16x32_bf16 v[86:89], v[174:177], v[206:209], v[86:89]
	v_mfma_f32_16x16x32_bf16 v[82:85], v[182:185], v[206:209], v[82:85]
	v_mfma_f32_16x16x32_bf16 v[70:73], v[174:177], v[222:225], v[70:73]
	v_mfma_f32_16x16x32_bf16 v[66:69], v[182:185], v[222:225], v[66:69]
	s_setprio 0
	s_barrier
	s_add_i32 s55, s55, s31
	v_lshl_add_u64 v[148:149], s[22:23], 0, v[0:1]
	s_mov_b32 m0, s55
	ds_read_b128 v[186:189], v164 offset:16384
	ds_read_b128 v[190:193], v164 offset:17408
	ds_read_b128 v[194:197], v164 offset:18432
	ds_read_b128 v[198:201], v164 offset:19456
	ds_read_b128 v[202:205], v164 offset:20480
	ds_read_b128 v[206:209], v164 offset:21504
	ds_read_b128 v[210:213], v164 offset:22528
	ds_read_b128 v[222:225], v164 offset:23552
	s_setprio 2
	global_load_lds_dwordx4 v[148:149], off
	s_add_i32 m0, s55, 0x2000
	s_add_u32 s56, s22, 0x40000
	v_lshl_add_u64 v[226:227], s[22:23], 0, v[134:135]
	s_addc_u32 s57, s23, 0
	s_add_i32 s55, s58, s31
	global_load_lds_dwordx4 v[226:227], off
	v_lshl_add_u64 v[228:229], s[56:57], 0, v[0:1]
	s_mov_b32 m0, s55
	v_lshl_add_u64 v[230:231], s[24:25], 0, v[132:133]
	global_load_lds_dwordx4 v[228:229], off
	v_lshl_add_u64 v[228:229], s[56:57], 0, v[134:135]
	s_add_i32 m0, s55, 0x2000
	s_nop 0
	global_load_lds_dwordx4 v[228:229], off
	v_lshl_add_u64 v[228:229], s[24:25], 0, v[130:131]
	s_mov_b32 m0, s19
	s_nop 0
	global_load_lds_dwordx4 v[228:229], off
	s_mov_b32 m0, s37
	s_nop 0
	global_load_lds_dwordx4 v[230:231], off
	s_setprio 0
	s_cmp_lg_u32 s98, 0
	s_cbranch_scc1 .Lrelax_ff1_w2
	s_waitcnt vmcnt(8)
.Lback_ff1_w2:
	s_waitcnt lgkmcnt(0)
	s_barrier
	s_setprio 1
	s_waitcnt lgkmcnt(0)
	v_mfma_f32_16x16x32_bf16 v[62:65], v[140:143], v[186:189], v[62:65]
	v_mfma_f32_16x16x32_bf16 v[58:61], v[154:157], v[186:189], v[58:61]
	v_mfma_f32_16x16x32_bf16 v[46:49], v[140:143], v[194:197], v[46:49]
	v_mfma_f32_16x16x32_bf16 v[42:45], v[154:157], v[194:197], v[42:45]
	v_mfma_f32_16x16x32_bf16 v[30:33], v[140:143], v[202:205], v[30:33]
	v_mfma_f32_16x16x32_bf16 v[26:29], v[154:157], v[202:205], v[26:29]
	v_mfma_f32_16x16x32_bf16 v[14:17], v[140:143], v[210:213], v[14:17]
	v_mfma_f32_16x16x32_bf16 v[10:13], v[154:157], v[210:213], v[10:13]
	v_mfma_f32_16x16x32_bf16 v[62:65], v[144:147], v[190:193], v[62:65]
	v_mfma_f32_16x16x32_bf16 v[58:61], v[166:169], v[190:193], v[58:61]
	v_mfma_f32_16x16x32_bf16 v[46:49], v[144:147], v[198:201], v[46:49]
	v_mfma_f32_16x16x32_bf16 v[42:45], v[166:169], v[198:201], v[42:45]
	v_mfma_f32_16x16x32_bf16 v[30:33], v[144:147], v[206:209], v[30:33]
	v_mfma_f32_16x16x32_bf16 v[26:29], v[166:169], v[206:209], v[26:29]
	v_mfma_f32_16x16x32_bf16 v[14:17], v[144:147], v[222:225], v[14:17]
	v_mfma_f32_16x16x32_bf16 v[10:13], v[166:169], v[222:225], v[10:13]
	s_setprio 0
	s_setprio 1
	v_mfma_f32_16x16x32_bf16 v[54:57], v[170:173], v[186:189], v[54:57]
	v_mfma_f32_16x16x32_bf16 v[50:53], v[178:181], v[186:189], v[50:53]
	v_mfma_f32_16x16x32_bf16 v[38:41], v[170:173], v[194:197], v[38:41]
	v_mfma_f32_16x16x32_bf16 v[34:37], v[178:181], v[194:197], v[34:37]
	v_mfma_f32_16x16x32_bf16 v[22:25], v[170:173], v[202:205], v[22:25]
	v_mfma_f32_16x16x32_bf16 v[18:21], v[178:181], v[202:205], v[18:21]
	v_mfma_f32_16x16x32_bf16 v[6:9], v[170:173], v[210:213], v[6:9]
	v_mfma_f32_16x16x32_bf16 v[2:5], v[178:181], v[210:213], v[2:5]
	v_mfma_f32_16x16x32_bf16 v[54:57], v[174:177], v[190:193], v[54:57]
	v_mfma_f32_16x16x32_bf16 v[50:53], v[182:185], v[190:193], v[50:53]
	v_mfma_f32_16x16x32_bf16 v[38:41], v[174:177], v[198:201], v[38:41]
	v_mfma_f32_16x16x32_bf16 v[34:37], v[182:185], v[198:201], v[34:37]
	v_mfma_f32_16x16x32_bf16 v[22:25], v[174:177], v[206:209], v[22:25]
	v_mfma_f32_16x16x32_bf16 v[18:21], v[182:185], v[206:209], v[18:21]
	v_mfma_f32_16x16x32_bf16 v[6:9], v[174:177], v[222:225], v[6:9]
	v_mfma_f32_16x16x32_bf16 v[2:5], v[182:185], v[222:225], v[2:5]
	s_setprio 0
	s_barrier
	s_add_i32 s55, 0, 0x18000
	v_add_u32_e32 v165, s55, v162
	s_add_i32 s56, 0, 0x1c000
	ds_read_b128 v[140:143], v165
	ds_read_b128 v[144:147], v165 offset:1024
	ds_read_b128 v[154:157], v165 offset:2048
	ds_read_b128 v[166:169], v165 offset:3072
	v_add_u32_e32 v165, s56, v162
	ds_read_b128 v[170:173], v165
	ds_read_b128 v[174:177], v165 offset:1024
	ds_read_b128 v[178:181], v165 offset:2048
	ds_read_b128 v[182:185], v165 offset:3072
	s_add_u32 s24, s24, 0x40000
	s_addc_u32 s25, s25, 0
	s_mov_b32 m0, s38
	v_lshl_add_u64 v[232:233], s[24:25], 0, v[130:131]
	ds_read_b128 v[186:189], v164 offset:32768
	ds_read_b128 v[190:193], v164 offset:33792
	ds_read_b128 v[194:197], v164 offset:34816
	ds_read_b128 v[198:201], v164 offset:35840
	ds_read_b128 v[202:205], v164 offset:36864
	ds_read_b128 v[206:209], v164 offset:37888
	ds_read_b128 v[210:213], v164 offset:38912
	ds_read_b128 v[222:225], v164 offset:39936
	s_setprio 2
	global_load_lds_dwordx4 v[232:233], off
	v_lshl_add_u64 v[232:233], s[24:25], 0, v[132:133]
	s_mov_b32 m0, s39
	s_nop 0
	global_load_lds_dwordx4 v[232:233], off
	s_setprio 0
	s_waitcnt vmcnt(8)
	s_waitcnt lgkmcnt(0)
	s_barrier
	s_setprio 1
	s_waitcnt lgkmcnt(0)
	v_mfma_f32_16x16x32_bf16 v[126:129], v[140:143], v[186:189], v[126:129]
	v_mfma_f32_16x16x32_bf16 v[122:125], v[154:157], v[186:189], v[122:125]
	v_mfma_f32_16x16x32_bf16 v[110:113], v[140:143], v[194:197], v[110:113]
	v_mfma_f32_16x16x32_bf16 v[106:109], v[154:157], v[194:197], v[106:109]
	v_mfma_f32_16x16x32_bf16 v[94:97], v[140:143], v[202:205], v[94:97]
	v_mfma_f32_16x16x32_bf16 v[90:93], v[154:157], v[202:205], v[90:93]
	v_mfma_f32_16x16x32_bf16 v[78:81], v[140:143], v[210:213], v[78:81]
	v_mfma_f32_16x16x32_bf16 v[74:77], v[154:157], v[210:213], v[74:77]
	v_mfma_f32_16x16x32_bf16 v[126:129], v[144:147], v[190:193], v[126:129]
	v_mfma_f32_16x16x32_bf16 v[122:125], v[166:169], v[190:193], v[122:125]
	v_mfma_f32_16x16x32_bf16 v[110:113], v[144:147], v[198:201], v[110:113]
	v_mfma_f32_16x16x32_bf16 v[106:109], v[166:169], v[198:201], v[106:109]
	v_mfma_f32_16x16x32_bf16 v[94:97], v[144:147], v[206:209], v[94:97]
	v_mfma_f32_16x16x32_bf16 v[90:93], v[166:169], v[206:209], v[90:93]
	v_mfma_f32_16x16x32_bf16 v[78:81], v[144:147], v[222:225], v[78:81]
	v_mfma_f32_16x16x32_bf16 v[74:77], v[166:169], v[222:225], v[74:77]
	s_setprio 0
	s_setprio 1
	v_mfma_f32_16x16x32_bf16 v[118:121], v[170:173], v[186:189], v[118:121]
	v_mfma_f32_16x16x32_bf16 v[114:117], v[178:181], v[186:189], v[114:117]
	v_mfma_f32_16x16x32_bf16 v[102:105], v[170:173], v[194:197], v[102:105]
	v_mfma_f32_16x16x32_bf16 v[98:101], v[178:181], v[194:197], v[98:101]
	v_mfma_f32_16x16x32_bf16 v[86:89], v[170:173], v[202:205], v[86:89]
	v_mfma_f32_16x16x32_bf16 v[82:85], v[178:181], v[202:205], v[82:85]
	v_mfma_f32_16x16x32_bf16 v[70:73], v[170:173], v[210:213], v[70:73]
	v_mfma_f32_16x16x32_bf16 v[66:69], v[178:181], v[210:213], v[66:69]
	v_mfma_f32_16x16x32_bf16 v[118:121], v[174:177], v[190:193], v[118:121]
	v_mfma_f32_16x16x32_bf16 v[114:117], v[182:185], v[190:193], v[114:117]
	v_mfma_f32_16x16x32_bf16 v[102:105], v[174:177], v[198:201], v[102:105]
	v_mfma_f32_16x16x32_bf16 v[98:101], v[182:185], v[198:201], v[98:101]
	v_mfma_f32_16x16x32_bf16 v[86:89], v[174:177], v[206:209], v[86:89]
	v_mfma_f32_16x16x32_bf16 v[82:85], v[182:185], v[206:209], v[82:85]
	v_mfma_f32_16x16x32_bf16 v[70:73], v[174:177], v[222:225], v[70:73]
	v_mfma_f32_16x16x32_bf16 v[66:69], v[182:185], v[222:225], v[66:69]
	s_setprio 0
	s_barrier
	s_add_i32 s24, s55, s31
	v_lshl_add_u64 v[148:149], v[148:149], 0, s[96:97]
	s_mov_b32 m0, s24
	ds_read_b128 v[186:189], v164 offset:49152
	ds_read_b128 v[190:193], v164 offset:50176
	ds_read_b128 v[194:197], v164 offset:51200
	ds_read_b128 v[198:201], v164 offset:52224
	ds_read_b128 v[202:205], v164 offset:53248
	ds_read_b128 v[206:209], v164 offset:54272
	ds_read_b128 v[210:213], v164 offset:55296
	ds_read_b128 v[222:225], v164 offset:56320
	s_setprio 2
	global_load_lds_dwordx4 v[148:149], off
	s_add_i32 m0, s24, 0x2000
	s_add_u32 s22, s22, 0x40080
	v_lshl_add_u64 v[148:149], v[226:227], 0, s[96:97]
	s_addc_u32 s23, s23, 0
	s_add_i32 s24, s56, s31
	global_load_lds_dwordx4 v[148:149], off
	v_lshl_add_u64 v[148:149], s[22:23], 0, v[0:1]
	s_mov_b32 m0, s24
	s_nop 0
	global_load_lds_dwordx4 v[148:149], off
	v_lshl_add_u64 v[148:149], s[22:23], 0, v[134:135]
	s_add_i32 m0, s24, 0x2000
	s_nop 0
	global_load_lds_dwordx4 v[148:149], off
	v_lshl_add_u64 v[148:149], v[228:229], 0, s[96:97]
	s_mov_b32 m0, s40
	s_nop 0
	global_load_lds_dwordx4 v[148:149], off
	v_lshl_add_u64 v[148:149], v[230:231], 0, s[96:97]
	s_mov_b32 m0, s41
	s_nop 0
	global_load_lds_dwordx4 v[148:149], off
	s_setprio 0
	s_waitcnt vmcnt(8)
	s_waitcnt lgkmcnt(0)
	s_barrier
	s_setprio 1
	s_waitcnt lgkmcnt(0)
	v_mfma_f32_16x16x32_bf16 v[62:65], v[140:143], v[186:189], v[62:65]
	v_mfma_f32_16x16x32_bf16 v[58:61], v[154:157], v[186:189], v[58:61]
	v_mfma_f32_16x16x32_bf16 v[46:49], v[140:143], v[194:197], v[46:49]
	v_mfma_f32_16x16x32_bf16 v[42:45], v[154:157], v[194:197], v[42:45]
	v_mfma_f32_16x16x32_bf16 v[30:33], v[140:143], v[202:205], v[30:33]
	v_mfma_f32_16x16x32_bf16 v[26:29], v[154:157], v[202:205], v[26:29]
	v_mfma_f32_16x16x32_bf16 v[14:17], v[140:143], v[210:213], v[14:17]
	v_mfma_f32_16x16x32_bf16 v[10:13], v[154:157], v[210:213], v[10:13]
	v_mfma_f32_16x16x32_bf16 v[62:65], v[144:147], v[190:193], v[62:65]
	v_mfma_f32_16x16x32_bf16 v[58:61], v[166:169], v[190:193], v[58:61]
	v_mfma_f32_16x16x32_bf16 v[46:49], v[144:147], v[198:201], v[46:49]
	v_mfma_f32_16x16x32_bf16 v[42:45], v[166:169], v[198:201], v[42:45]
	v_mfma_f32_16x16x32_bf16 v[30:33], v[144:147], v[206:209], v[30:33]
	v_mfma_f32_16x16x32_bf16 v[26:29], v[166:169], v[206:209], v[26:29]
	v_mfma_f32_16x16x32_bf16 v[14:17], v[144:147], v[222:225], v[14:17]
	v_mfma_f32_16x16x32_bf16 v[10:13], v[166:169], v[222:225], v[10:13]
	s_setprio 0
	s_setprio 1
	v_mfma_f32_16x16x32_bf16 v[54:57], v[170:173], v[186:189], v[54:57]
	v_mfma_f32_16x16x32_bf16 v[50:53], v[178:181], v[186:189], v[50:53]
	v_mfma_f32_16x16x32_bf16 v[38:41], v[170:173], v[194:197], v[38:41]
	v_mfma_f32_16x16x32_bf16 v[34:37], v[178:181], v[194:197], v[34:37]
	v_mfma_f32_16x16x32_bf16 v[22:25], v[170:173], v[202:205], v[22:25]
	v_mfma_f32_16x16x32_bf16 v[18:21], v[178:181], v[202:205], v[18:21]
	v_mfma_f32_16x16x32_bf16 v[6:9], v[170:173], v[210:213], v[6:9]
	v_mfma_f32_16x16x32_bf16 v[2:5], v[178:181], v[210:213], v[2:5]
	v_mfma_f32_16x16x32_bf16 v[54:57], v[174:177], v[190:193], v[54:57]
	v_mfma_f32_16x16x32_bf16 v[50:53], v[182:185], v[190:193], v[50:53]
	v_mfma_f32_16x16x32_bf16 v[38:41], v[174:177], v[198:201], v[38:41]
	v_mfma_f32_16x16x32_bf16 v[34:37], v[182:185], v[198:201], v[34:37]
	v_mfma_f32_16x16x32_bf16 v[22:25], v[174:177], v[206:209], v[22:25]
	v_mfma_f32_16x16x32_bf16 v[18:21], v[182:185], v[206:209], v[18:21]
	v_mfma_f32_16x16x32_bf16 v[6:9], v[174:177], v[222:225], v[6:9]
	v_mfma_f32_16x16x32_bf16 v[2:5], v[182:185], v[222:225], v[2:5]
	s_setprio 0
	s_barrier
	s_add_i32 s49, s49, 2
	s_add_u32 s47, s47, 0x100
	s_addc_u32 s48, s48, 0
	s_add_u32 s20, s20, 0x100
	s_addc_u32 s21, s21, 0
	s_cmp_gt_u32 s49, 13
	s_cbranch_scc0 .LBB0_43
	s_and_b64 vcc, exec, s[8:9]
	s_movk_i32 s46, 0xd000
	s_movk_i32 s47, 0xec00
	s_cbranch_vccz .LBB0_46
	s_barrier

.LBB0_79:
	s_add_u32 s22, s20, 0xfffc0080
	s_addc_u32 s23, s21, -1
	s_add_i32 s55, 0, 0x10000
	s_cmp_eq_u32 s49, 12
	s_cselect_b32 s25, s13, s23
	s_cselect_b32 s24, s45, s22
	s_cselect_b32 s23, s11, s48
	s_cselect_b32 s22, s46, s47
	s_add_i32 s58, 0, 0x14000
	v_add_u32_e32 v134, s55, v176
	v_add_u32_e32 v179, s58, v176
	ds_read_b128 v[122:125], v134
	ds_read_b128 v[126:129], v134 offset:1024
	ds_read_b128 v[130:133], v134 offset:2048
	ds_read_b128 v[134:137], v134 offset:3072
	ds_read_b128 v[146:149], v179
	ds_read_b128 v[154:157], v179 offset:1024
	ds_read_b128 v[172:175], v179 offset:2048
	ds_read_b128 v[180:183], v179 offset:3072
	v_lshl_add_u64 v[212:213], s[20:21], 0, v[170:171]
	s_add_i32 m0, s19, 0xc000
	ds_read_b128 v[184:187], v178
	ds_read_b128 v[188:191], v178 offset:1024
	ds_read_b128 v[192:195], v178 offset:2048
	ds_read_b128 v[196:199], v178 offset:3072
	ds_read_b128 v[200:203], v178 offset:4096
	ds_read_b128 v[204:207], v178 offset:5120
	ds_read_b128 v[208:211], v178 offset:6144
	ds_read_b128 v[222:225], v178 offset:7168
	s_setprio 2
	global_load_lds_dwordx4 v[212:213], off
	v_lshl_add_u64 v[212:213], s[20:21], 0, v[168:169]
	s_add_i32 m0, s19, 0xe000
	s_nop 0
	global_load_lds_dwordx4 v[212:213], off
	s_setprio 0
	s_cmp_lg_u32 s98, 0
	s_cbranch_scc1 .Lrelax_g2_w1
	s_waitcnt vmcnt(8)
.Lback_g2_w1:
	s_waitcnt lgkmcnt(0)
	s_barrier
	s_setprio 1
	s_waitcnt lgkmcnt(0)
	v_mfma_f32_16x16x32_bf16 v[142:145], v[122:125], v[184:187], v[142:145]
	v_mfma_f32_16x16x32_bf16 v[138:141], v[130:133], v[184:187], v[138:141]
	v_mfma_f32_16x16x32_bf16 v[118:121], v[122:125], v[192:195], v[118:121]
	v_mfma_f32_16x16x32_bf16 v[106:109], v[130:133], v[192:195], v[106:109]
	v_mfma_f32_16x16x32_bf16 v[98:101], v[122:125], v[200:203], v[98:101]
	v_mfma_f32_16x16x32_bf16 v[90:93], v[130:133], v[200:203], v[90:93]
	v_mfma_f32_16x16x32_bf16 v[86:89], v[122:125], v[208:211], v[86:89]
	v_mfma_f32_16x16x32_bf16 v[74:77], v[130:133], v[208:211], v[74:77]
	v_mfma_f32_16x16x32_bf16 v[142:145], v[126:129], v[188:191], v[142:145]
	v_mfma_f32_16x16x32_bf16 v[138:141], v[134:137], v[188:191], v[138:141]
	v_mfma_f32_16x16x32_bf16 v[118:121], v[126:129], v[196:199], v[118:121]
	v_mfma_f32_16x16x32_bf16 v[106:109], v[134:137], v[196:199], v[106:109]
	v_mfma_f32_16x16x32_bf16 v[98:101], v[126:129], v[204:207], v[98:101]
	v_mfma_f32_16x16x32_bf16 v[90:93], v[134:137], v[204:207], v[90:93]
	v_mfma_f32_16x16x32_bf16 v[86:89], v[126:129], v[222:225], v[86:89]
	v_mfma_f32_16x16x32_bf16 v[74:77], v[134:137], v[222:225], v[74:77]
	s_setprio 0
	s_setprio 1
	v_mfma_f32_16x16x32_bf16 v[114:117], v[146:149], v[184:187], v[114:117]
	v_mfma_f32_16x16x32_bf16 v[110:113], v[172:175], v[184:187], v[110:113]
	v_mfma_f32_16x16x32_bf16 v[102:105], v[146:149], v[192:195], v[102:105]
	v_mfma_f32_16x16x32_bf16 v[94:97], v[172:175], v[192:195], v[94:97]
	v_mfma_f32_16x16x32_bf16 v[82:85], v[146:149], v[200:203], v[82:85]
	v_mfma_f32_16x16x32_bf16 v[78:81], v[172:175], v[200:203], v[78:81]
	v_mfma_f32_16x16x32_bf16 v[70:73], v[146:149], v[208:211], v[70:73]
	v_mfma_f32_16x16x32_bf16 v[66:69], v[172:175], v[208:211], v[66:69]
	v_mfma_f32_16x16x32_bf16 v[114:117], v[154:157], v[188:191], v[114:117]
	v_mfma_f32_16x16x32_bf16 v[110:113], v[180:183], v[188:191], v[110:113]
	v_mfma_f32_16x16x32_bf16 v[102:105], v[154:157], v[196:199], v[102:105]
	v_mfma_f32_16x16x32_bf16 v[94:97], v[180:183], v[196:199], v[94:97]
	v_mfma_f32_16x16x32_bf16 v[82:85], v[154:157], v[204:207], v[82:85]
	v_mfma_f32_16x16x32_bf16 v[78:81], v[180:183], v[204:207], v[78:81]
	v_mfma_f32_16x16x32_bf16 v[70:73], v[154:157], v[222:225], v[70:73]
	v_mfma_f32_16x16x32_bf16 v[66:69], v[180:183], v[222:225], v[66:69]
	s_setprio 0
	s_barrier
	s_add_i32 s55, s55, s29
	v_lshl_add_u64 v[212:213], s[22:23], 0, v[0:1]
	s_mov_b32 m0, s55
	ds_read_b128 v[184:187], v178 offset:16384
	ds_read_b128 v[188:191], v178 offset:17408
	ds_read_b128 v[192:195], v178 offset:18432
	ds_read_b128 v[196:199], v178 offset:19456
	ds_read_b128 v[200:203], v178 offset:20480
	ds_read_b128 v[204:207], v178 offset:21504
	ds_read_b128 v[208:211], v178 offset:22528
	ds_read_b128 v[222:225], v178 offset:23552
	s_setprio 2
	global_load_lds_dwordx4 v[212:213], off
	s_add_i32 m0, s55, 0x2000
	s_add_u32 s56, s22, 0x40000
	v_lshl_add_u64 v[226:227], s[22:23], 0, v[166:167]
	s_addc_u32 s57, s23, 0
	s_add_i32 s55, s58, s29
	global_load_lds_dwordx4 v[226:227], off
	v_lshl_add_u64 v[228:229], s[56:57], 0, v[0:1]
	s_mov_b32 m0, s55
	v_lshl_add_u64 v[230:231], s[24:25], 0, v[164:165]
	global_load_lds_dwordx4 v[228:229], off
	v_lshl_add_u64 v[228:229], s[56:57], 0, v[166:167]
	s_add_i32 m0, s55, 0x2000
	s_nop 0
	global_load_lds_dwordx4 v[228:229], off
	v_lshl_add_u64 v[228:229], s[24:25], 0, v[162:163]
	s_mov_b32 m0, s19
	s_nop 0
	global_load_lds_dwordx4 v[228:229], off
	s_mov_b32 m0, s30
	s_nop 0
	global_load_lds_dwordx4 v[230:231], off
	s_setprio 0
	s_cmp_lg_u32 s98, 0
	s_cbranch_scc1 .Lrelax_g2_w2
	s_waitcnt vmcnt(8)
.Lback_g2_w2:
	s_waitcnt lgkmcnt(0)
	s_barrier
	s_setprio 1
	s_waitcnt lgkmcnt(0)
	v_mfma_f32_16x16x32_bf16 v[62:65], v[122:125], v[184:187], v[62:65]
	v_mfma_f32_16x16x32_bf16 v[58:61], v[130:133], v[184:187], v[58:61]
	v_mfma_f32_16x16x32_bf16 v[54:57], v[122:125], v[192:195], v[54:57]
	v_mfma_f32_16x16x32_bf16 v[42:45], v[130:133], v[192:195], v[42:45]
	v_mfma_f32_16x16x32_bf16 v[34:37], v[122:125], v[200:203], v[34:37]
	v_mfma_f32_16x16x32_bf16 v[26:29], v[130:133], v[200:203], v[26:29]
	v_mfma_f32_16x16x32_bf16 v[22:25], v[122:125], v[208:211], v[22:25]
	v_mfma_f32_16x16x32_bf16 v[10:13], v[130:133], v[208:211], v[10:13]
	v_mfma_f32_16x16x32_bf16 v[62:65], v[126:129], v[188:191], v[62:65]
	v_mfma_f32_16x16x32_bf16 v[58:61], v[134:137], v[188:191], v[58:61]
	v_mfma_f32_16x16x32_bf16 v[54:57], v[126:129], v[196:199], v[54:57]
	v_mfma_f32_16x16x32_bf16 v[42:45], v[134:137], v[196:199], v[42:45]
	v_mfma_f32_16x16x32_bf16 v[34:37], v[126:129], v[204:207], v[34:37]
	v_mfma_f32_16x16x32_bf16 v[26:29], v[134:137], v[204:207], v[26:29]
	v_mfma_f32_16x16x32_bf16 v[22:25], v[126:129], v[222:225], v[22:25]
	v_mfma_f32_16x16x32_bf16 v[10:13], v[134:137], v[222:225], v[10:13]
	s_setprio 0
	s_setprio 1
	v_mfma_f32_16x16x32_bf16 v[50:53], v[146:149], v[184:187], v[50:53]
	v_mfma_f32_16x16x32_bf16 v[46:49], v[172:175], v[184:187], v[46:49]
	v_mfma_f32_16x16x32_bf16 v[38:41], v[146:149], v[192:195], v[38:41]
	v_mfma_f32_16x16x32_bf16 v[30:33], v[172:175], v[192:195], v[30:33]
	v_mfma_f32_16x16x32_bf16 v[18:21], v[146:149], v[200:203], v[18:21]
	v_mfma_f32_16x16x32_bf16 v[14:17], v[172:175], v[200:203], v[14:17]
	v_mfma_f32_16x16x32_bf16 v[6:9], v[146:149], v[208:211], v[6:9]
	v_mfma_f32_16x16x32_bf16 v[2:5], v[172:175], v[208:211], v[2:5]
	v_mfma_f32_16x16x32_bf16 v[50:53], v[154:157], v[188:191], v[50:53]
	v_mfma_f32_16x16x32_bf16 v[46:49], v[180:183], v[188:191], v[46:49]
	v_mfma_f32_16x16x32_bf16 v[38:41], v[154:157], v[196:199], v[38:41]
	v_mfma_f32_16x16x32_bf16 v[30:33], v[180:183], v[196:199], v[30:33]
	v_mfma_f32_16x16x32_bf16 v[18:21], v[154:157], v[204:207], v[18:21]
	v_mfma_f32_16x16x32_bf16 v[14:17], v[180:183], v[204:207], v[14:17]
	v_mfma_f32_16x16x32_bf16 v[6:9], v[154:157], v[222:225], v[6:9]
	v_mfma_f32_16x16x32_bf16 v[2:5], v[180:183], v[222:225], v[2:5]
	s_setprio 0
	s_barrier
	s_add_i32 s55, 0, 0x18000
	s_add_i32 s56, 0, 0x1c000
	v_add_u32_e32 v134, s55, v176
	v_add_u32_e32 v179, s56, v176
	ds_read_b128 v[122:125], v134
	ds_read_b128 v[126:129], v134 offset:1024
	ds_read_b128 v[130:133], v134 offset:2048
	ds_read_b128 v[134:137], v134 offset:3072
	ds_read_b128 v[146:149], v179
	ds_read_b128 v[154:157], v179 offset:1024
	ds_read_b128 v[172:175], v179 offset:2048
	ds_read_b128 v[180:183], v179 offset:3072
	s_add_u32 s24, s24, 0x40000
	s_addc_u32 s25, s25, 0
	s_mov_b32 m0, s31
	v_lshl_add_u64 v[232:233], s[24:25], 0, v[162:163]
	ds_read_b128 v[184:187], v178 offset:32768
	ds_read_b128 v[188:191], v178 offset:33792
	ds_read_b128 v[192:195], v178 offset:34816
	ds_read_b128 v[196:199], v178 offset:35840
	ds_read_b128 v[200:203], v178 offset:36864
	ds_read_b128 v[204:207], v178 offset:37888
	ds_read_b128 v[208:211], v178 offset:38912
	ds_read_b128 v[222:225], v178 offset:39936
	s_setprio 2
	global_load_lds_dwordx4 v[232:233], off
	v_lshl_add_u64 v[232:233], s[24:25], 0, v[164:165]
	s_mov_b32 m0, s37
	s_nop 0
	global_load_lds_dwordx4 v[232:233], off
	s_setprio 0
	s_waitcnt vmcnt(8)
	s_waitcnt lgkmcnt(0)
	s_barrier
	s_setprio 1
	s_waitcnt lgkmcnt(0)
	v_mfma_f32_16x16x32_bf16 v[142:145], v[122:125], v[184:187], v[142:145]
	v_mfma_f32_16x16x32_bf16 v[138:141], v[130:133], v[184:187], v[138:141]
	v_mfma_f32_16x16x32_bf16 v[118:121], v[122:125], v[192:195], v[118:121]
	v_mfma_f32_16x16x32_bf16 v[106:109], v[130:133], v[192:195], v[106:109]
	v_mfma_f32_16x16x32_bf16 v[98:101], v[122:125], v[200:203], v[98:101]
	v_mfma_f32_16x16x32_bf16 v[90:93], v[130:133], v[200:203], v[90:93]
	v_mfma_f32_16x16x32_bf16 v[86:89], v[122:125], v[208:211], v[86:89]
	v_mfma_f32_16x16x32_bf16 v[74:77], v[130:133], v[208:211], v[74:77]
	v_mfma_f32_16x16x32_bf16 v[142:145], v[126:129], v[188:191], v[142:145]
	v_mfma_f32_16x16x32_bf16 v[138:141], v[134:137], v[188:191], v[138:141]
	v_mfma_f32_16x16x32_bf16 v[118:121], v[126:129], v[196:199], v[118:121]
	v_mfma_f32_16x16x32_bf16 v[106:109], v[134:137], v[196:199], v[106:109]
	v_mfma_f32_16x16x32_bf16 v[98:101], v[126:129], v[204:207], v[98:101]
	v_mfma_f32_16x16x32_bf16 v[90:93], v[134:137], v[204:207], v[90:93]
	v_mfma_f32_16x16x32_bf16 v[86:89], v[126:129], v[222:225], v[86:89]
	v_mfma_f32_16x16x32_bf16 v[74:77], v[134:137], v[222:225], v[74:77]
	s_setprio 0
	s_setprio 1
	v_mfma_f32_16x16x32_bf16 v[114:117], v[146:149], v[184:187], v[114:117]
	v_mfma_f32_16x16x32_bf16 v[110:113], v[172:175], v[184:187], v[110:113]
	v_mfma_f32_16x16x32_bf16 v[102:105], v[146:149], v[192:195], v[102:105]
	v_mfma_f32_16x16x32_bf16 v[94:97], v[172:175], v[192:195], v[94:97]
	v_mfma_f32_16x16x32_bf16 v[82:85], v[146:149], v[200:203], v[82:85]
	v_mfma_f32_16x16x32_bf16 v[78:81], v[172:175], v[200:203], v[78:81]
	v_mfma_f32_16x16x32_bf16 v[70:73], v[146:149], v[208:211], v[70:73]
	v_mfma_f32_16x16x32_bf16 v[66:69], v[172:175], v[208:211], v[66:69]
	v_mfma_f32_16x16x32_bf16 v[114:117], v[154:157], v[188:191], v[114:117]
	v_mfma_f32_16x16x32_bf16 v[110:113], v[180:183], v[188:191], v[110:113]
	v_mfma_f32_16x16x32_bf16 v[102:105], v[154:157], v[196:199], v[102:105]
	v_mfma_f32_16x16x32_bf16 v[94:97], v[180:183], v[196:199], v[94:97]
	v_mfma_f32_16x16x32_bf16 v[82:85], v[154:157], v[204:207], v[82:85]
	v_mfma_f32_16x16x32_bf16 v[78:81], v[180:183], v[204:207], v[78:81]
	v_mfma_f32_16x16x32_bf16 v[70:73], v[154:157], v[222:225], v[70:73]
	v_mfma_f32_16x16x32_bf16 v[66:69], v[180:183], v[222:225], v[66:69]
	s_setprio 0
	s_barrier
	s_add_i32 s24, s55, s29
	v_lshl_add_u64 v[212:213], v[212:213], 0, s[96:97]
	s_mov_b32 m0, s24
	ds_read_b128 v[184:187], v178 offset:49152
	ds_read_b128 v[188:191], v178 offset:50176
	ds_read_b128 v[192:195], v178 offset:51200
	ds_read_b128 v[196:199], v178 offset:52224
	ds_read_b128 v[200:203], v178 offset:53248
	ds_read_b128 v[204:207], v178 offset:54272
	ds_read_b128 v[208:211], v178 offset:55296
	ds_read_b128 v[222:225], v178 offset:56320
	s_setprio 2
	global_load_lds_dwordx4 v[212:213], off
	s_add_i32 m0, s24, 0x2000
	s_add_u32 s22, s22, 0x40080
	v_lshl_add_u64 v[212:213], v[226:227], 0, s[96:97]
	s_addc_u32 s23, s23, 0
	s_add_i32 s24, s56, s29
	global_load_lds_dwordx4 v[212:213], off
	v_lshl_add_u64 v[212:213], s[22:23], 0, v[0:1]
	s_mov_b32 m0, s24
	s_nop 0
	global_load_lds_dwordx4 v[212:213], off
	v_lshl_add_u64 v[212:213], s[22:23], 0, v[166:167]
	s_add_i32 m0, s24, 0x2000
	s_nop 0
	global_load_lds_dwordx4 v[212:213], off
	v_lshl_add_u64 v[212:213], v[228:229], 0, s[96:97]
	s_mov_b32 m0, s40
	s_nop 0
	global_load_lds_dwordx4 v[212:213], off
	v_lshl_add_u64 v[212:213], v[230:231], 0, s[96:97]
	s_mov_b32 m0, s41
	s_nop 0
	global_load_lds_dwordx4 v[212:213], off
	s_setprio 0
	s_waitcnt vmcnt(8)
	s_waitcnt lgkmcnt(0)
	s_barrier
	s_setprio 1
	s_waitcnt lgkmcnt(0)
	v_mfma_f32_16x16x32_bf16 v[62:65], v[122:125], v[184:187], v[62:65]
	v_mfma_f32_16x16x32_bf16 v[58:61], v[130:133], v[184:187], v[58:61]
	v_mfma_f32_16x16x32_bf16 v[54:57], v[122:125], v[192:195], v[54:57]
	v_mfma_f32_16x16x32_bf16 v[42:45], v[130:133], v[192:195], v[42:45]
	v_mfma_f32_16x16x32_bf16 v[34:37], v[122:125], v[200:203], v[34:37]
	v_mfma_f32_16x16x32_bf16 v[26:29], v[130:133], v[200:203], v[26:29]
	v_mfma_f32_16x16x32_bf16 v[22:25], v[122:125], v[208:211], v[22:25]
	v_mfma_f32_16x16x32_bf16 v[10:13], v[130:133], v[208:211], v[10:13]
	v_mfma_f32_16x16x32_bf16 v[62:65], v[126:129], v[188:191], v[62:65]
	v_mfma_f32_16x16x32_bf16 v[58:61], v[134:137], v[188:191], v[58:61]
	v_mfma_f32_16x16x32_bf16 v[54:57], v[126:129], v[196:199], v[54:57]
	v_mfma_f32_16x16x32_bf16 v[42:45], v[134:137], v[196:199], v[42:45]
	v_mfma_f32_16x16x32_bf16 v[34:37], v[126:129], v[204:207], v[34:37]
	v_mfma_f32_16x16x32_bf16 v[26:29], v[134:137], v[204:207], v[26:29]
	v_mfma_f32_16x16x32_bf16 v[22:25], v[126:129], v[222:225], v[22:25]
	v_mfma_f32_16x16x32_bf16 v[10:13], v[134:137], v[222:225], v[10:13]
	s_setprio 0
	s_setprio 1
	v_mfma_f32_16x16x32_bf16 v[50:53], v[146:149], v[184:187], v[50:53]
	v_mfma_f32_16x16x32_bf16 v[46:49], v[172:175], v[184:187], v[46:49]
	v_mfma_f32_16x16x32_bf16 v[38:41], v[146:149], v[192:195], v[38:41]
	v_mfma_f32_16x16x32_bf16 v[30:33], v[172:175], v[192:195], v[30:33]
	v_mfma_f32_16x16x32_bf16 v[18:21], v[146:149], v[200:203], v[18:21]
	v_mfma_f32_16x16x32_bf16 v[14:17], v[172:175], v[200:203], v[14:17]
	v_mfma_f32_16x16x32_bf16 v[6:9], v[146:149], v[208:211], v[6:9]
	v_mfma_f32_16x16x32_bf16 v[2:5], v[172:175], v[208:211], v[2:5]
	v_mfma_f32_16x16x32_bf16 v[50:53], v[154:157], v[188:191], v[50:53]
	v_mfma_f32_16x16x32_bf16 v[46:49], v[180:183], v[188:191], v[46:49]
	v_mfma_f32_16x16x32_bf16 v[38:41], v[154:157], v[196:199], v[38:41]
	v_mfma_f32_16x16x32_bf16 v[30:33], v[180:183], v[196:199], v[30:33]
	v_mfma_f32_16x16x32_bf16 v[18:21], v[154:157], v[204:207], v[18:21]
	v_mfma_f32_16x16x32_bf16 v[14:17], v[180:183], v[204:207], v[14:17]
	v_mfma_f32_16x16x32_bf16 v[6:9], v[154:157], v[222:225], v[6:9]
	v_mfma_f32_16x16x32_bf16 v[2:5], v[180:183], v[222:225], v[2:5]
	s_setprio 0
	s_barrier
	s_add_i32 s49, s49, 2
	s_add_u32 s47, s47, 0x100
	s_addc_u32 s48, s48, 0
	s_add_u32 s20, s20, 0x100
	s_addc_u32 s21, s21, 0
	s_cmp_gt_u32 s49, 13
	s_cbranch_scc0 .LBB0_79
	s_and_b64 vcc, exec, s[8:9]
	s_movk_i32 s46, 0xd000
	s_movk_i32 s47, 0xec00
	s_cbranch_vccz .LBB0_82
	s_barrier

.LBB0_105:
	s_add_u32 s22, s20, 0xfffc0080
	s_addc_u32 s23, s21, -1
	s_add_i32 s55, 0, 0x10000
	s_cmp_eq_u32 s49, 12
	s_cselect_b32 s25, s13, s23
	s_cselect_b32 s24, s45, s22
	s_cselect_b32 s23, s11, s48
	s_cselect_b32 s22, s46, s47
	s_add_i32 s58, 0, 0x14000
	v_add_u32_e32 v142, s55, v176
	v_add_u32_e32 v179, s58, v176
	ds_read_b128 v[130:133], v142
	ds_read_b128 v[134:137], v142 offset:1024
	ds_read_b128 v[138:141], v142 offset:2048
	ds_read_b128 v[142:145], v142 offset:3072
	ds_read_b128 v[146:149], v179
	ds_read_b128 v[154:157], v179 offset:1024
	ds_read_b128 v[172:175], v179 offset:2048
	ds_read_b128 v[180:183], v179 offset:3072
	v_lshl_add_u64 v[212:213], s[20:21], 0, v[170:171]
	s_add_i32 m0, s19, 0xc000
	ds_read_b128 v[184:187], v178
	ds_read_b128 v[188:191], v178 offset:1024
	ds_read_b128 v[192:195], v178 offset:2048
	ds_read_b128 v[196:199], v178 offset:3072
	ds_read_b128 v[200:203], v178 offset:4096
	ds_read_b128 v[204:207], v178 offset:5120
	ds_read_b128 v[208:211], v178 offset:6144
	ds_read_b128 v[222:225], v178 offset:7168
	s_setprio 2
	global_load_lds_dwordx4 v[212:213], off
	v_lshl_add_u64 v[212:213], s[20:21], 0, v[168:169]
	s_add_i32 m0, s19, 0xe000
	s_nop 0
	global_load_lds_dwordx4 v[212:213], off
	s_setprio 0
	s_cmp_lg_u32 s98, 0
	s_cbranch_scc1 .Lrelax_g3_w1
	s_waitcnt vmcnt(8)
.Lback_g3_w1:
	s_waitcnt lgkmcnt(0)
	s_barrier
	s_setprio 1
	s_waitcnt lgkmcnt(0)
	v_mfma_f32_16x16x32_bf16 v[126:129], v[130:133], v[184:187], v[126:129]
	v_mfma_f32_16x16x32_bf16 v[122:125], v[138:141], v[184:187], v[122:125]
	v_mfma_f32_16x16x32_bf16 v[110:113], v[130:133], v[192:195], v[110:113]
	v_mfma_f32_16x16x32_bf16 v[106:109], v[138:141], v[192:195], v[106:109]
	v_mfma_f32_16x16x32_bf16 v[94:97], v[130:133], v[200:203], v[94:97]
	v_mfma_f32_16x16x32_bf16 v[90:93], v[138:141], v[200:203], v[90:93]
	v_mfma_f32_16x16x32_bf16 v[78:81], v[130:133], v[208:211], v[78:81]
	v_mfma_f32_16x16x32_bf16 v[74:77], v[138:141], v[208:211], v[74:77]
	v_mfma_f32_16x16x32_bf16 v[126:129], v[134:137], v[188:191], v[126:129]
	v_mfma_f32_16x16x32_bf16 v[122:125], v[142:145], v[188:191], v[122:125]
	v_mfma_f32_16x16x32_bf16 v[110:113], v[134:137], v[196:199], v[110:113]
	v_mfma_f32_16x16x32_bf16 v[106:109], v[142:145], v[196:199], v[106:109]
	v_mfma_f32_16x16x32_bf16 v[94:97], v[134:137], v[204:207], v[94:97]
	v_mfma_f32_16x16x32_bf16 v[90:93], v[142:145], v[204:207], v[90:93]
	v_mfma_f32_16x16x32_bf16 v[78:81], v[134:137], v[222:225], v[78:81]
	v_mfma_f32_16x16x32_bf16 v[74:77], v[142:145], v[222:225], v[74:77]
	s_setprio 0
	s_setprio 1
	v_mfma_f32_16x16x32_bf16 v[118:121], v[146:149], v[184:187], v[118:121]
	v_mfma_f32_16x16x32_bf16 v[114:117], v[172:175], v[184:187], v[114:117]
	v_mfma_f32_16x16x32_bf16 v[102:105], v[146:149], v[192:195], v[102:105]
	v_mfma_f32_16x16x32_bf16 v[98:101], v[172:175], v[192:195], v[98:101]
	v_mfma_f32_16x16x32_bf16 v[86:89], v[146:149], v[200:203], v[86:89]
	v_mfma_f32_16x16x32_bf16 v[82:85], v[172:175], v[200:203], v[82:85]
	v_mfma_f32_16x16x32_bf16 v[70:73], v[146:149], v[208:211], v[70:73]
	v_mfma_f32_16x16x32_bf16 v[66:69], v[172:175], v[208:211], v[66:69]
	v_mfma_f32_16x16x32_bf16 v[118:121], v[154:157], v[188:191], v[118:121]
	v_mfma_f32_16x16x32_bf16 v[114:117], v[180:183], v[188:191], v[114:117]
	v_mfma_f32_16x16x32_bf16 v[102:105], v[154:157], v[196:199], v[102:105]
	v_mfma_f32_16x16x32_bf16 v[98:101], v[180:183], v[196:199], v[98:101]
	v_mfma_f32_16x16x32_bf16 v[86:89], v[154:157], v[204:207], v[86:89]
	v_mfma_f32_16x16x32_bf16 v[82:85], v[180:183], v[204:207], v[82:85]
	v_mfma_f32_16x16x32_bf16 v[70:73], v[154:157], v[222:225], v[70:73]
	v_mfma_f32_16x16x32_bf16 v[66:69], v[180:183], v[222:225], v[66:69]
	s_setprio 0
	s_barrier
	s_add_i32 s55, s55, s29
	v_lshl_add_u64 v[212:213], s[22:23], 0, v[0:1]
	s_mov_b32 m0, s55
	ds_read_b128 v[184:187], v178 offset:16384
	ds_read_b128 v[188:191], v178 offset:17408
	ds_read_b128 v[192:195], v178 offset:18432
	ds_read_b128 v[196:199], v178 offset:19456
	ds_read_b128 v[200:203], v178 offset:20480
	ds_read_b128 v[204:207], v178 offset:21504
	ds_read_b128 v[208:211], v178 offset:22528
	ds_read_b128 v[222:225], v178 offset:23552
	s_setprio 2
	global_load_lds_dwordx4 v[212:213], off
	s_add_i32 m0, s55, 0x2000
	s_add_u32 s56, s22, 0x40000
	v_lshl_add_u64 v[226:227], s[22:23], 0, v[166:167]
	s_addc_u32 s57, s23, 0
	s_add_i32 s55, s58, s29
	global_load_lds_dwordx4 v[226:227], off
	v_lshl_add_u64 v[228:229], s[56:57], 0, v[0:1]
	s_mov_b32 m0, s55
	v_lshl_add_u64 v[230:231], s[24:25], 0, v[164:165]
	global_load_lds_dwordx4 v[228:229], off
	v_lshl_add_u64 v[228:229], s[56:57], 0, v[166:167]
	s_add_i32 m0, s55, 0x2000
	s_nop 0
	global_load_lds_dwordx4 v[228:229], off
	v_lshl_add_u64 v[228:229], s[24:25], 0, v[162:163]
	s_mov_b32 m0, s19
	s_nop 0
	global_load_lds_dwordx4 v[228:229], off
	s_mov_b32 m0, s30
	s_nop 0
	global_load_lds_dwordx4 v[230:231], off
	s_setprio 0
	s_cmp_lg_u32 s98, 0
	s_cbranch_scc1 .Lrelax_g3_w2
	s_waitcnt vmcnt(8)
.Lback_g3_w2:
	s_waitcnt lgkmcnt(0)
	s_barrier
	s_setprio 1
	s_waitcnt lgkmcnt(0)
	v_mfma_f32_16x16x32_bf16 v[62:65], v[130:133], v[184:187], v[62:65]
	v_mfma_f32_16x16x32_bf16 v[58:61], v[138:141], v[184:187], v[58:61]
	v_mfma_f32_16x16x32_bf16 v[46:49], v[130:133], v[192:195], v[46:49]
	v_mfma_f32_16x16x32_bf16 v[42:45], v[138:141], v[192:195], v[42:45]
	v_mfma_f32_16x16x32_bf16 v[30:33], v[130:133], v[200:203], v[30:33]
	v_mfma_f32_16x16x32_bf16 v[26:29], v[138:141], v[200:203], v[26:29]
	v_mfma_f32_16x16x32_bf16 v[14:17], v[130:133], v[208:211], v[14:17]
	v_mfma_f32_16x16x32_bf16 v[10:13], v[138:141], v[208:211], v[10:13]
	v_mfma_f32_16x16x32_bf16 v[62:65], v[134:137], v[188:191], v[62:65]
	v_mfma_f32_16x16x32_bf16 v[58:61], v[142:145], v[188:191], v[58:61]
	v_mfma_f32_16x16x32_bf16 v[46:49], v[134:137], v[196:199], v[46:49]
	v_mfma_f32_16x16x32_bf16 v[42:45], v[142:145], v[196:199], v[42:45]
	v_mfma_f32_16x16x32_bf16 v[30:33], v[134:137], v[204:207], v[30:33]
	v_mfma_f32_16x16x32_bf16 v[26:29], v[142:145], v[204:207], v[26:29]
	v_mfma_f32_16x16x32_bf16 v[14:17], v[134:137], v[222:225], v[14:17]
	v_mfma_f32_16x16x32_bf16 v[10:13], v[142:145], v[222:225], v[10:13]
	s_setprio 0
	s_setprio 1
	v_mfma_f32_16x16x32_bf16 v[54:57], v[146:149], v[184:187], v[54:57]
	v_mfma_f32_16x16x32_bf16 v[50:53], v[172:175], v[184:187], v[50:53]
	v_mfma_f32_16x16x32_bf16 v[38:41], v[146:149], v[192:195], v[38:41]
	v_mfma_f32_16x16x32_bf16 v[34:37], v[172:175], v[192:195], v[34:37]
	v_mfma_f32_16x16x32_bf16 v[22:25], v[146:149], v[200:203], v[22:25]
	v_mfma_f32_16x16x32_bf16 v[18:21], v[172:175], v[200:203], v[18:21]
	v_mfma_f32_16x16x32_bf16 v[6:9], v[146:149], v[208:211], v[6:9]
	v_mfma_f32_16x16x32_bf16 v[2:5], v[172:175], v[208:211], v[2:5]
	v_mfma_f32_16x16x32_bf16 v[54:57], v[154:157], v[188:191], v[54:57]
	v_mfma_f32_16x16x32_bf16 v[50:53], v[180:183], v[188:191], v[50:53]
	v_mfma_f32_16x16x32_bf16 v[38:41], v[154:157], v[196:199], v[38:41]
	v_mfma_f32_16x16x32_bf16 v[34:37], v[180:183], v[196:199], v[34:37]
	v_mfma_f32_16x16x32_bf16 v[22:25], v[154:157], v[204:207], v[22:25]
	v_mfma_f32_16x16x32_bf16 v[18:21], v[180:183], v[204:207], v[18:21]
	v_mfma_f32_16x16x32_bf16 v[6:9], v[154:157], v[222:225], v[6:9]
	v_mfma_f32_16x16x32_bf16 v[2:5], v[180:183], v[222:225], v[2:5]
	s_setprio 0
	s_barrier
	s_add_i32 s55, 0, 0x18000
	s_add_i32 s56, 0, 0x1c000
	v_add_u32_e32 v142, s55, v176
	v_add_u32_e32 v179, s56, v176
	ds_read_b128 v[130:133], v142
	ds_read_b128 v[134:137], v142 offset:1024
	ds_read_b128 v[138:141], v142 offset:2048
	ds_read_b128 v[142:145], v142 offset:3072
	ds_read_b128 v[146:149], v179
	ds_read_b128 v[154:157], v179 offset:1024
	ds_read_b128 v[172:175], v179 offset:2048
	ds_read_b128 v[180:183], v179 offset:3072
	s_add_u32 s24, s24, 0x40000
	s_addc_u32 s25, s25, 0
	s_mov_b32 m0, s31
	v_lshl_add_u64 v[232:233], s[24:25], 0, v[162:163]
	ds_read_b128 v[184:187], v178 offset:32768
	ds_read_b128 v[188:191], v178 offset:33792
	ds_read_b128 v[192:195], v178 offset:34816
	ds_read_b128 v[196:199], v178 offset:35840
	ds_read_b128 v[200:203], v178 offset:36864
	ds_read_b128 v[204:207], v178 offset:37888
	ds_read_b128 v[208:211], v178 offset:38912
	ds_read_b128 v[222:225], v178 offset:39936
	s_setprio 2
	global_load_lds_dwordx4 v[232:233], off
	v_lshl_add_u64 v[232:233], s[24:25], 0, v[164:165]
	s_mov_b32 m0, s37
	s_nop 0
	global_load_lds_dwordx4 v[232:233], off
	s_setprio 0
	s_waitcnt vmcnt(8)
	s_waitcnt lgkmcnt(0)
	s_barrier
	s_setprio 1
	s_waitcnt lgkmcnt(0)
	v_mfma_f32_16x16x32_bf16 v[126:129], v[130:133], v[184:187], v[126:129]
	v_mfma_f32_16x16x32_bf16 v[122:125], v[138:141], v[184:187], v[122:125]
	v_mfma_f32_16x16x32_bf16 v[110:113], v[130:133], v[192:195], v[110:113]
	v_mfma_f32_16x16x32_bf16 v[106:109], v[138:141], v[192:195], v[106:109]
	v_mfma_f32_16x16x32_bf16 v[94:97], v[130:133], v[200:203], v[94:97]
	v_mfma_f32_16x16x32_bf16 v[90:93], v[138:141], v[200:203], v[90:93]
	v_mfma_f32_16x16x32_bf16 v[78:81], v[130:133], v[208:211], v[78:81]
	v_mfma_f32_16x16x32_bf16 v[74:77], v[138:141], v[208:211], v[74:77]
	v_mfma_f32_16x16x32_bf16 v[126:129], v[134:137], v[188:191], v[126:129]
	v_mfma_f32_16x16x32_bf16 v[122:125], v[142:145], v[188:191], v[122:125]
	v_mfma_f32_16x16x32_bf16 v[110:113], v[134:137], v[196:199], v[110:113]
	v_mfma_f32_16x16x32_bf16 v[106:109], v[142:145], v[196:199], v[106:109]
	v_mfma_f32_16x16x32_bf16 v[94:97], v[134:137], v[204:207], v[94:97]
	v_mfma_f32_16x16x32_bf16 v[90:93], v[142:145], v[204:207], v[90:93]
	v_mfma_f32_16x16x32_bf16 v[78:81], v[134:137], v[222:225], v[78:81]
	v_mfma_f32_16x16x32_bf16 v[74:77], v[142:145], v[222:225], v[74:77]
	s_setprio 0
	s_setprio 1
	v_mfma_f32_16x16x32_bf16 v[118:121], v[146:149], v[184:187], v[118:121]
	v_mfma_f32_16x16x32_bf16 v[114:117], v[172:175], v[184:187], v[114:117]
	v_mfma_f32_16x16x32_bf16 v[102:105], v[146:149], v[192:195], v[102:105]
	v_mfma_f32_16x16x32_bf16 v[98:101], v[172:175], v[192:195], v[98:101]
	v_mfma_f32_16x16x32_bf16 v[86:89], v[146:149], v[200:203], v[86:89]
	v_mfma_f32_16x16x32_bf16 v[82:85], v[172:175], v[200:203], v[82:85]
	v_mfma_f32_16x16x32_bf16 v[70:73], v[146:149], v[208:211], v[70:73]
	v_mfma_f32_16x16x32_bf16 v[66:69], v[172:175], v[208:211], v[66:69]
	v_mfma_f32_16x16x32_bf16 v[118:121], v[154:157], v[188:191], v[118:121]
	v_mfma_f32_16x16x32_bf16 v[114:117], v[180:183], v[188:191], v[114:117]
	v_mfma_f32_16x16x32_bf16 v[102:105], v[154:157], v[196:199], v[102:105]
	v_mfma_f32_16x16x32_bf16 v[98:101], v[180:183], v[196:199], v[98:101]
	v_mfma_f32_16x16x32_bf16 v[86:89], v[154:157], v[204:207], v[86:89]
	v_mfma_f32_16x16x32_bf16 v[82:85], v[180:183], v[204:207], v[82:85]
	v_mfma_f32_16x16x32_bf16 v[70:73], v[154:157], v[222:225], v[70:73]
	v_mfma_f32_16x16x32_bf16 v[66:69], v[180:183], v[222:225], v[66:69]
	s_setprio 0
	s_barrier
	s_add_i32 s24, s55, s29
	v_lshl_add_u64 v[212:213], v[212:213], 0, s[96:97]
	s_mov_b32 m0, s24
	ds_read_b128 v[184:187], v178 offset:49152
	ds_read_b128 v[188:191], v178 offset:50176
	ds_read_b128 v[192:195], v178 offset:51200
	ds_read_b128 v[196:199], v178 offset:52224
	ds_read_b128 v[200:203], v178 offset:53248
	ds_read_b128 v[204:207], v178 offset:54272
	ds_read_b128 v[208:211], v178 offset:55296
	ds_read_b128 v[222:225], v178 offset:56320
	s_setprio 2
	global_load_lds_dwordx4 v[212:213], off
	s_add_i32 m0, s24, 0x2000
	s_add_u32 s22, s22, 0x40080
	v_lshl_add_u64 v[212:213], v[226:227], 0, s[96:97]
	s_addc_u32 s23, s23, 0
	s_add_i32 s24, s56, s29
	global_load_lds_dwordx4 v[212:213], off
	v_lshl_add_u64 v[212:213], s[22:23], 0, v[0:1]
	s_mov_b32 m0, s24
	s_nop 0
	global_load_lds_dwordx4 v[212:213], off
	v_lshl_add_u64 v[212:213], s[22:23], 0, v[166:167]
	s_add_i32 m0, s24, 0x2000
	s_nop 0
	global_load_lds_dwordx4 v[212:213], off
	v_lshl_add_u64 v[212:213], v[228:229], 0, s[96:97]
	s_mov_b32 m0, s40
	s_nop 0
	global_load_lds_dwordx4 v[212:213], off
	v_lshl_add_u64 v[212:213], v[230:231], 0, s[96:97]
	s_mov_b32 m0, s41
	s_nop 0
	global_load_lds_dwordx4 v[212:213], off
	s_setprio 0
	s_waitcnt vmcnt(8)
	s_waitcnt lgkmcnt(0)
	s_barrier
	s_setprio 1
	s_waitcnt lgkmcnt(0)
	v_mfma_f32_16x16x32_bf16 v[62:65], v[130:133], v[184:187], v[62:65]
	v_mfma_f32_16x16x32_bf16 v[58:61], v[138:141], v[184:187], v[58:61]
	v_mfma_f32_16x16x32_bf16 v[46:49], v[130:133], v[192:195], v[46:49]
	v_mfma_f32_16x16x32_bf16 v[42:45], v[138:141], v[192:195], v[42:45]
	v_mfma_f32_16x16x32_bf16 v[30:33], v[130:133], v[200:203], v[30:33]
	v_mfma_f32_16x16x32_bf16 v[26:29], v[138:141], v[200:203], v[26:29]
	v_mfma_f32_16x16x32_bf16 v[14:17], v[130:133], v[208:211], v[14:17]
	v_mfma_f32_16x16x32_bf16 v[10:13], v[138:141], v[208:211], v[10:13]
	v_mfma_f32_16x16x32_bf16 v[62:65], v[134:137], v[188:191], v[62:65]
	v_mfma_f32_16x16x32_bf16 v[58:61], v[142:145], v[188:191], v[58:61]
	v_mfma_f32_16x16x32_bf16 v[46:49], v[134:137], v[196:199], v[46:49]
	v_mfma_f32_16x16x32_bf16 v[42:45], v[142:145], v[196:199], v[42:45]
	v_mfma_f32_16x16x32_bf16 v[30:33], v[134:137], v[204:207], v[30:33]
	v_mfma_f32_16x16x32_bf16 v[26:29], v[142:145], v[204:207], v[26:29]
	v_mfma_f32_16x16x32_bf16 v[14:17], v[134:137], v[222:225], v[14:17]
	v_mfma_f32_16x16x32_bf16 v[10:13], v[142:145], v[222:225], v[10:13]
	s_setprio 0
	s_setprio 1
	v_mfma_f32_16x16x32_bf16 v[54:57], v[146:149], v[184:187], v[54:57]
	v_mfma_f32_16x16x32_bf16 v[50:53], v[172:175], v[184:187], v[50:53]
	v_mfma_f32_16x16x32_bf16 v[38:41], v[146:149], v[192:195], v[38:41]
	v_mfma_f32_16x16x32_bf16 v[34:37], v[172:175], v[192:195], v[34:37]
	v_mfma_f32_16x16x32_bf16 v[22:25], v[146:149], v[200:203], v[22:25]
	v_mfma_f32_16x16x32_bf16 v[18:21], v[172:175], v[200:203], v[18:21]
	v_mfma_f32_16x16x32_bf16 v[6:9], v[146:149], v[208:211], v[6:9]
	v_mfma_f32_16x16x32_bf16 v[2:5], v[172:175], v[208:211], v[2:5]
	v_mfma_f32_16x16x32_bf16 v[54:57], v[154:157], v[188:191], v[54:57]
	v_mfma_f32_16x16x32_bf16 v[50:53], v[180:183], v[188:191], v[50:53]
	v_mfma_f32_16x16x32_bf16 v[38:41], v[154:157], v[196:199], v[38:41]
	v_mfma_f32_16x16x32_bf16 v[34:37], v[180:183], v[196:199], v[34:37]
	v_mfma_f32_16x16x32_bf16 v[22:25], v[154:157], v[204:207], v[22:25]
	v_mfma_f32_16x16x32_bf16 v[18:21], v[180:183], v[204:207], v[18:21]
	v_mfma_f32_16x16x32_bf16 v[6:9], v[154:157], v[222:225], v[6:9]
	v_mfma_f32_16x16x32_bf16 v[2:5], v[180:183], v[222:225], v[2:5]
	s_setprio 0
	s_barrier
	s_add_i32 s49, s49, 2
	s_add_u32 s47, s47, 0x100
	s_addc_u32 s48, s48, 0
	s_add_u32 s20, s20, 0x100
	s_addc_u32 s21, s21, 0
	s_cmp_gt_u32 s49, 13
	s_cbranch_scc0 .LBB0_105
	s_and_b64 vcc, exec, s[8:9]
	s_movk_i32 s46, 0xd000
	s_movk_i32 s47, 0xec00
	s_cbranch_vccz .LBB0_108
	s_barrier

.LBB0_353:
	s_add_u32 s22, s20, 0xfffc0080
	s_addc_u32 s23, s21, -1
	s_add_i32 s55, 0, 0x10000
	s_cmp_eq_u32 s49, 12
	s_cselect_b32 s25, s13, s23
	s_cselect_b32 s24, s45, s22
	v_add_u32_e32 v140, s55, v143
	s_cselect_b32 s23, s11, s48
	s_cselect_b32 s22, s46, s47
	s_add_i32 s58, 0, 0x14000
	ds_read_b128 v[162:165], v140
	ds_read_b128 v[166:169], v140 offset:1024
	ds_read_b128 v[170:173], v140 offset:2048
	ds_read_b128 v[174:177], v140 offset:3072
	v_add_u32_e32 v140, s58, v143
	ds_read_b128 v[178:181], v140
	ds_read_b128 v[182:185], v140 offset:1024
	ds_read_b128 v[186:189], v140 offset:2048
	ds_read_b128 v[190:193], v140 offset:3072
	v_lshl_add_u64 v[140:141], s[20:21], 0, v[138:139]
	s_add_i32 m0, s19, 0xc000
	ds_read_b128 v[194:197], v145
	ds_read_b128 v[198:201], v145 offset:1024
	ds_read_b128 v[202:205], v145 offset:2048
	ds_read_b128 v[206:209], v145 offset:3072
	ds_read_b128 v[210:213], v145 offset:4096
	ds_read_b128 v[222:225], v145 offset:5120
	ds_read_b128 v[226:229], v145 offset:6144
	ds_read_b128 v[230:233], v145 offset:7168
	s_setprio 2
	global_load_lds_dwordx4 v[140:141], off
	v_lshl_add_u64 v[140:141], s[20:21], 0, v[136:137]
	s_add_i32 m0, s19, 0xe000
	s_nop 0
	global_load_lds_dwordx4 v[140:141], off
	s_setprio 0
	s_cmp_lg_u32 s98, 0
	s_cbranch_scc1 .Lrelax_g4_w1
	s_waitcnt vmcnt(8)
.Lback_g4_w1:
	s_waitcnt lgkmcnt(0)
	s_barrier
	s_setprio 1
	s_waitcnt lgkmcnt(0)
	v_mfma_f32_16x16x32_bf16 v[126:129], v[162:165], v[194:197], v[126:129]
	v_mfma_f32_16x16x32_bf16 v[122:125], v[170:173], v[194:197], v[122:125]
	v_mfma_f32_16x16x32_bf16 v[114:117], v[162:165], v[202:205], v[114:117]
	v_mfma_f32_16x16x32_bf16 v[106:109], v[170:173], v[202:205], v[106:109]
	v_mfma_f32_16x16x32_bf16 v[98:101], v[162:165], v[210:213], v[98:101]
	v_mfma_f32_16x16x32_bf16 v[90:93], v[170:173], v[210:213], v[90:93]
	v_mfma_f32_16x16x32_bf16 v[82:85], v[162:165], v[226:229], v[82:85]
	v_mfma_f32_16x16x32_bf16 v[74:77], v[170:173], v[226:229], v[74:77]
	v_mfma_f32_16x16x32_bf16 v[126:129], v[166:169], v[198:201], v[126:129]
	v_mfma_f32_16x16x32_bf16 v[122:125], v[174:177], v[198:201], v[122:125]
	v_mfma_f32_16x16x32_bf16 v[114:117], v[166:169], v[206:209], v[114:117]
	v_mfma_f32_16x16x32_bf16 v[106:109], v[174:177], v[206:209], v[106:109]
	v_mfma_f32_16x16x32_bf16 v[98:101], v[166:169], v[222:225], v[98:101]
	v_mfma_f32_16x16x32_bf16 v[90:93], v[174:177], v[222:225], v[90:93]
	v_mfma_f32_16x16x32_bf16 v[82:85], v[166:169], v[230:233], v[82:85]
	v_mfma_f32_16x16x32_bf16 v[74:77], v[174:177], v[230:233], v[74:77]
	s_setprio 0
	s_setprio 1
	v_mfma_f32_16x16x32_bf16 v[118:121], v[178:181], v[194:197], v[118:121]
	v_mfma_f32_16x16x32_bf16 v[110:113], v[186:189], v[194:197], v[110:113]
	v_mfma_f32_16x16x32_bf16 v[102:105], v[178:181], v[202:205], v[102:105]
	v_mfma_f32_16x16x32_bf16 v[94:97], v[186:189], v[202:205], v[94:97]
	v_mfma_f32_16x16x32_bf16 v[86:89], v[178:181], v[210:213], v[86:89]
	v_mfma_f32_16x16x32_bf16 v[78:81], v[186:189], v[210:213], v[78:81]
	v_mfma_f32_16x16x32_bf16 v[70:73], v[178:181], v[226:229], v[70:73]
	v_mfma_f32_16x16x32_bf16 v[66:69], v[186:189], v[226:229], v[66:69]
	v_mfma_f32_16x16x32_bf16 v[118:121], v[182:185], v[198:201], v[118:121]
	v_mfma_f32_16x16x32_bf16 v[110:113], v[190:193], v[198:201], v[110:113]
	v_mfma_f32_16x16x32_bf16 v[102:105], v[182:185], v[206:209], v[102:105]
	v_mfma_f32_16x16x32_bf16 v[94:97], v[190:193], v[206:209], v[94:97]
	v_mfma_f32_16x16x32_bf16 v[86:89], v[182:185], v[222:225], v[86:89]
	v_mfma_f32_16x16x32_bf16 v[78:81], v[190:193], v[222:225], v[78:81]
	v_mfma_f32_16x16x32_bf16 v[70:73], v[182:185], v[230:233], v[70:73]
	v_mfma_f32_16x16x32_bf16 v[66:69], v[190:193], v[230:233], v[66:69]
	s_setprio 0
	s_barrier
	s_add_i32 s55, s55, s30
	v_lshl_add_u64 v[140:141], s[22:23], 0, v[0:1]
	s_mov_b32 m0, s55
	ds_read_b128 v[194:197], v145 offset:16384
	ds_read_b128 v[198:201], v145 offset:17408
	ds_read_b128 v[202:205], v145 offset:18432
	ds_read_b128 v[206:209], v145 offset:19456
	ds_read_b128 v[210:213], v145 offset:20480
	ds_read_b128 v[222:225], v145 offset:21504
	ds_read_b128 v[226:229], v145 offset:22528
	ds_read_b128 v[230:233], v145 offset:23552
	s_setprio 2
	global_load_lds_dwordx4 v[140:141], off
	s_add_i32 m0, s55, 0x2000
	s_add_u32 s56, s22, 0x40000
	v_lshl_add_u64 v[146:147], s[22:23], 0, v[130:131]
	s_addc_u32 s57, s23, 0
	s_add_i32 s55, s58, s30
	global_load_lds_dwordx4 v[146:147], off
	v_lshl_add_u64 v[148:149], s[56:57], 0, v[0:1]
	s_mov_b32 m0, s55
	v_lshl_add_u64 v[154:155], s[24:25], 0, v[132:133]
	global_load_lds_dwordx4 v[148:149], off
	v_lshl_add_u64 v[148:149], s[56:57], 0, v[130:131]
	s_add_i32 m0, s55, 0x2000
	s_nop 0
	global_load_lds_dwordx4 v[148:149], off
	v_lshl_add_u64 v[148:149], s[24:25], 0, v[134:135]
	s_mov_b32 m0, s19
	s_nop 0
	global_load_lds_dwordx4 v[148:149], off
	s_mov_b32 m0, s37
	s_nop 0
	global_load_lds_dwordx4 v[154:155], off
	s_setprio 0
	s_cmp_lg_u32 s98, 0
	s_cbranch_scc1 .Lrelax_g4_w2
	s_waitcnt vmcnt(8)
.Lback_g4_w2:
	s_waitcnt lgkmcnt(0)
	s_barrier
	s_setprio 1
	s_waitcnt lgkmcnt(0)
	v_mfma_f32_16x16x32_bf16 v[62:65], v[162:165], v[194:197], v[62:65]
	v_mfma_f32_16x16x32_bf16 v[58:61], v[170:173], v[194:197], v[58:61]
	v_mfma_f32_16x16x32_bf16 v[50:53], v[162:165], v[202:205], v[50:53]
	v_mfma_f32_16x16x32_bf16 v[42:45], v[170:173], v[202:205], v[42:45]
	v_mfma_f32_16x16x32_bf16 v[34:37], v[162:165], v[210:213], v[34:37]
	v_mfma_f32_16x16x32_bf16 v[26:29], v[170:173], v[210:213], v[26:29]
	v_mfma_f32_16x16x32_bf16 v[18:21], v[162:165], v[226:229], v[18:21]
	v_mfma_f32_16x16x32_bf16 v[10:13], v[170:173], v[226:229], v[10:13]
	v_mfma_f32_16x16x32_bf16 v[62:65], v[166:169], v[198:201], v[62:65]
	v_mfma_f32_16x16x32_bf16 v[58:61], v[174:177], v[198:201], v[58:61]
	v_mfma_f32_16x16x32_bf16 v[50:53], v[166:169], v[206:209], v[50:53]
	v_mfma_f32_16x16x32_bf16 v[42:45], v[174:177], v[206:209], v[42:45]
	v_mfma_f32_16x16x32_bf16 v[34:37], v[166:169], v[222:225], v[34:37]
	v_mfma_f32_16x16x32_bf16 v[26:29], v[174:177], v[222:225], v[26:29]
	v_mfma_f32_16x16x32_bf16 v[18:21], v[166:169], v[230:233], v[18:21]
	v_mfma_f32_16x16x32_bf16 v[10:13], v[174:177], v[230:233], v[10:13]
	s_setprio 0
	s_setprio 1
	v_mfma_f32_16x16x32_bf16 v[54:57], v[178:181], v[194:197], v[54:57]
	v_mfma_f32_16x16x32_bf16 v[46:49], v[186:189], v[194:197], v[46:49]
	v_mfma_f32_16x16x32_bf16 v[38:41], v[178:181], v[202:205], v[38:41]
	v_mfma_f32_16x16x32_bf16 v[30:33], v[186:189], v[202:205], v[30:33]
	v_mfma_f32_16x16x32_bf16 v[22:25], v[178:181], v[210:213], v[22:25]
	v_mfma_f32_16x16x32_bf16 v[14:17], v[186:189], v[210:213], v[14:17]
	v_mfma_f32_16x16x32_bf16 v[6:9], v[178:181], v[226:229], v[6:9]
	v_mfma_f32_16x16x32_bf16 v[2:5], v[186:189], v[226:229], v[2:5]
	v_mfma_f32_16x16x32_bf16 v[54:57], v[182:185], v[198:201], v[54:57]
	v_mfma_f32_16x16x32_bf16 v[46:49], v[190:193], v[198:201], v[46:49]
	v_mfma_f32_16x16x32_bf16 v[38:41], v[182:185], v[206:209], v[38:41]
	v_mfma_f32_16x16x32_bf16 v[30:33], v[190:193], v[206:209], v[30:33]
	v_mfma_f32_16x16x32_bf16 v[22:25], v[182:185], v[222:225], v[22:25]
	v_mfma_f32_16x16x32_bf16 v[14:17], v[190:193], v[222:225], v[14:17]
	v_mfma_f32_16x16x32_bf16 v[6:9], v[182:185], v[230:233], v[6:9]
	v_mfma_f32_16x16x32_bf16 v[2:5], v[190:193], v[230:233], v[2:5]
	s_setprio 0
	s_barrier
	s_add_i32 s55, 0, 0x18000
	v_add_u32_e32 v156, s55, v143
	s_add_i32 s56, 0, 0x1c000
	ds_read_b128 v[162:165], v156
	ds_read_b128 v[166:169], v156 offset:1024
	ds_read_b128 v[170:173], v156 offset:2048
	ds_read_b128 v[174:177], v156 offset:3072
	v_add_u32_e32 v156, s56, v143
	ds_read_b128 v[178:181], v156
	ds_read_b128 v[182:185], v156 offset:1024
	ds_read_b128 v[186:189], v156 offset:2048
	ds_read_b128 v[190:193], v156 offset:3072
	s_add_u32 s24, s24, 0x40000
	s_addc_u32 s25, s25, 0
	s_mov_b32 m0, s38
	v_lshl_add_u64 v[156:157], s[24:25], 0, v[134:135]
	ds_read_b128 v[194:197], v145 offset:32768
	ds_read_b128 v[198:201], v145 offset:33792
	ds_read_b128 v[202:205], v145 offset:34816
	ds_read_b128 v[206:209], v145 offset:35840
	ds_read_b128 v[210:213], v145 offset:36864
	ds_read_b128 v[222:225], v145 offset:37888
	ds_read_b128 v[226:229], v145 offset:38912
	ds_read_b128 v[230:233], v145 offset:39936
	s_setprio 2
	global_load_lds_dwordx4 v[156:157], off
	v_lshl_add_u64 v[156:157], s[24:25], 0, v[132:133]
	s_mov_b32 m0, s39
	s_nop 0
	global_load_lds_dwordx4 v[156:157], off
	s_setprio 0
	s_waitcnt vmcnt(8)
	s_waitcnt lgkmcnt(0)
	s_barrier
	s_setprio 1
	s_waitcnt lgkmcnt(0)
	v_mfma_f32_16x16x32_bf16 v[126:129], v[162:165], v[194:197], v[126:129]
	v_mfma_f32_16x16x32_bf16 v[122:125], v[170:173], v[194:197], v[122:125]
	v_mfma_f32_16x16x32_bf16 v[114:117], v[162:165], v[202:205], v[114:117]
	v_mfma_f32_16x16x32_bf16 v[106:109], v[170:173], v[202:205], v[106:109]
	v_mfma_f32_16x16x32_bf16 v[98:101], v[162:165], v[210:213], v[98:101]
	v_mfma_f32_16x16x32_bf16 v[90:93], v[170:173], v[210:213], v[90:93]
	v_mfma_f32_16x16x32_bf16 v[82:85], v[162:165], v[226:229], v[82:85]
	v_mfma_f32_16x16x32_bf16 v[74:77], v[170:173], v[226:229], v[74:77]
	v_mfma_f32_16x16x32_bf16 v[126:129], v[166:169], v[198:201], v[126:129]
	v_mfma_f32_16x16x32_bf16 v[122:125], v[174:177], v[198:201], v[122:125]
	v_mfma_f32_16x16x32_bf16 v[114:117], v[166:169], v[206:209], v[114:117]
	v_mfma_f32_16x16x32_bf16 v[106:109], v[174:177], v[206:209], v[106:109]
	v_mfma_f32_16x16x32_bf16 v[98:101], v[166:169], v[222:225], v[98:101]
	v_mfma_f32_16x16x32_bf16 v[90:93], v[174:177], v[222:225], v[90:93]
	v_mfma_f32_16x16x32_bf16 v[82:85], v[166:169], v[230:233], v[82:85]
	v_mfma_f32_16x16x32_bf16 v[74:77], v[174:177], v[230:233], v[74:77]
	s_setprio 0
	s_setprio 1
	v_mfma_f32_16x16x32_bf16 v[118:121], v[178:181], v[194:197], v[118:121]
	v_mfma_f32_16x16x32_bf16 v[110:113], v[186:189], v[194:197], v[110:113]
	v_mfma_f32_16x16x32_bf16 v[102:105], v[178:181], v[202:205], v[102:105]
	v_mfma_f32_16x16x32_bf16 v[94:97], v[186:189], v[202:205], v[94:97]
	v_mfma_f32_16x16x32_bf16 v[86:89], v[178:181], v[210:213], v[86:89]
	v_mfma_f32_16x16x32_bf16 v[78:81], v[186:189], v[210:213], v[78:81]
	v_mfma_f32_16x16x32_bf16 v[70:73], v[178:181], v[226:229], v[70:73]
	v_mfma_f32_16x16x32_bf16 v[66:69], v[186:189], v[226:229], v[66:69]
	v_mfma_f32_16x16x32_bf16 v[118:121], v[182:185], v[198:201], v[118:121]
	v_mfma_f32_16x16x32_bf16 v[110:113], v[190:193], v[198:201], v[110:113]
	v_mfma_f32_16x16x32_bf16 v[102:105], v[182:185], v[206:209], v[102:105]
	v_mfma_f32_16x16x32_bf16 v[94:97], v[190:193], v[206:209], v[94:97]
	v_mfma_f32_16x16x32_bf16 v[86:89], v[182:185], v[222:225], v[86:89]
	v_mfma_f32_16x16x32_bf16 v[78:81], v[190:193], v[222:225], v[78:81]
	v_mfma_f32_16x16x32_bf16 v[70:73], v[182:185], v[230:233], v[70:73]
	v_mfma_f32_16x16x32_bf16 v[66:69], v[190:193], v[230:233], v[66:69]
	s_setprio 0
	s_barrier
	s_add_i32 s24, s55, s30
	v_lshl_add_u64 v[140:141], v[140:141], 0, s[96:97]
	s_mov_b32 m0, s24
	ds_read_b128 v[194:197], v145 offset:49152
	ds_read_b128 v[198:201], v145 offset:50176
	ds_read_b128 v[202:205], v145 offset:51200
	ds_read_b128 v[206:209], v145 offset:52224
	ds_read_b128 v[210:213], v145 offset:53248
	ds_read_b128 v[222:225], v145 offset:54272
	ds_read_b128 v[226:229], v145 offset:55296
	ds_read_b128 v[230:233], v145 offset:56320
	s_setprio 2
	global_load_lds_dwordx4 v[140:141], off
	s_add_i32 m0, s24, 0x2000
	s_add_u32 s22, s22, 0x40080
	v_lshl_add_u64 v[140:141], v[146:147], 0, s[96:97]
	s_addc_u32 s23, s23, 0
	s_add_i32 s24, s56, s30
	global_load_lds_dwordx4 v[140:141], off
	v_lshl_add_u64 v[140:141], s[22:23], 0, v[0:1]
	s_mov_b32 m0, s24
	s_nop 0
	global_load_lds_dwordx4 v[140:141], off
	v_lshl_add_u64 v[140:141], s[22:23], 0, v[130:131]
	s_add_i32 m0, s24, 0x2000
	s_nop 0
	global_load_lds_dwordx4 v[140:141], off
	v_lshl_add_u64 v[140:141], v[148:149], 0, s[96:97]
	s_mov_b32 m0, s40
	s_nop 0
	global_load_lds_dwordx4 v[140:141], off
	v_lshl_add_u64 v[140:141], v[154:155], 0, s[96:97]
	s_mov_b32 m0, s41
	s_nop 0
	global_load_lds_dwordx4 v[140:141], off
	s_setprio 0
	s_waitcnt vmcnt(8)
	s_waitcnt lgkmcnt(0)
	s_barrier
	s_setprio 1
	s_waitcnt lgkmcnt(0)
	v_mfma_f32_16x16x32_bf16 v[62:65], v[162:165], v[194:197], v[62:65]
	v_mfma_f32_16x16x32_bf16 v[58:61], v[170:173], v[194:197], v[58:61]
	v_mfma_f32_16x16x32_bf16 v[50:53], v[162:165], v[202:205], v[50:53]
	v_mfma_f32_16x16x32_bf16 v[42:45], v[170:173], v[202:205], v[42:45]
	v_mfma_f32_16x16x32_bf16 v[34:37], v[162:165], v[210:213], v[34:37]
	v_mfma_f32_16x16x32_bf16 v[26:29], v[170:173], v[210:213], v[26:29]
	v_mfma_f32_16x16x32_bf16 v[18:21], v[162:165], v[226:229], v[18:21]
	v_mfma_f32_16x16x32_bf16 v[10:13], v[170:173], v[226:229], v[10:13]
	v_mfma_f32_16x16x32_bf16 v[62:65], v[166:169], v[198:201], v[62:65]
	v_mfma_f32_16x16x32_bf16 v[58:61], v[174:177], v[198:201], v[58:61]
	v_mfma_f32_16x16x32_bf16 v[50:53], v[166:169], v[206:209], v[50:53]
	v_mfma_f32_16x16x32_bf16 v[42:45], v[174:177], v[206:209], v[42:45]
	v_mfma_f32_16x16x32_bf16 v[34:37], v[166:169], v[222:225], v[34:37]
	v_mfma_f32_16x16x32_bf16 v[26:29], v[174:177], v[222:225], v[26:29]
	v_mfma_f32_16x16x32_bf16 v[18:21], v[166:169], v[230:233], v[18:21]
	v_mfma_f32_16x16x32_bf16 v[10:13], v[174:177], v[230:233], v[10:13]
	s_setprio 0
	s_setprio 1
	v_mfma_f32_16x16x32_bf16 v[54:57], v[178:181], v[194:197], v[54:57]
	v_mfma_f32_16x16x32_bf16 v[46:49], v[186:189], v[194:197], v[46:49]
	v_mfma_f32_16x16x32_bf16 v[38:41], v[178:181], v[202:205], v[38:41]
	v_mfma_f32_16x16x32_bf16 v[30:33], v[186:189], v[202:205], v[30:33]
	v_mfma_f32_16x16x32_bf16 v[22:25], v[178:181], v[210:213], v[22:25]
	v_mfma_f32_16x16x32_bf16 v[14:17], v[186:189], v[210:213], v[14:17]
	v_mfma_f32_16x16x32_bf16 v[6:9], v[178:181], v[226:229], v[6:9]
	v_mfma_f32_16x16x32_bf16 v[2:5], v[186:189], v[226:229], v[2:5]
	v_mfma_f32_16x16x32_bf16 v[54:57], v[182:185], v[198:201], v[54:57]
	v_mfma_f32_16x16x32_bf16 v[46:49], v[190:193], v[198:201], v[46:49]
	v_mfma_f32_16x16x32_bf16 v[38:41], v[182:185], v[206:209], v[38:41]
	v_mfma_f32_16x16x32_bf16 v[30:33], v[190:193], v[206:209], v[30:33]
	v_mfma_f32_16x16x32_bf16 v[22:25], v[182:185], v[222:225], v[22:25]
	v_mfma_f32_16x16x32_bf16 v[14:17], v[190:193], v[222:225], v[14:17]
	v_mfma_f32_16x16x32_bf16 v[6:9], v[182:185], v[230:233], v[6:9]
	v_mfma_f32_16x16x32_bf16 v[2:5], v[190:193], v[230:233], v[2:5]
	s_setprio 0
	s_barrier
	s_add_i32 s49, s49, 2
	s_add_u32 s47, s47, 0x100
	s_addc_u32 s48, s48, 0
	s_add_u32 s20, s20, 0x100
	s_addc_u32 s21, s21, 0
	s_cmp_gt_u32 s49, 13
	s_cbranch_scc0 .LBB0_353
	s_and_b64 vcc, exec, s[8:9]
	s_cbranch_vccz .LBB0_356
	s_barrier

.LBB0_381:
	s_add_u32 s22, s20, 0xfff00080
	s_addc_u32 s23, s21, -1
	s_add_i32 s57, 0, 0x10000
	s_cmp_eq_u32 s56, 60
	s_cselect_b32 s25, s13, s23
	s_cselect_b32 s24, s47, s22
	s_cselect_b32 s23, s11, s55
	s_cselect_b32 s22, s48, s49
	s_add_i32 s60, 0, 0x14000
	v_add_u32_e32 v134, s57, v176
	v_add_u32_e32 v179, s60, v176
	ds_read_b128 v[122:125], v134
	ds_read_b128 v[126:129], v134 offset:1024
	ds_read_b128 v[130:133], v134 offset:2048
	ds_read_b128 v[134:137], v134 offset:3072
	ds_read_b128 v[146:149], v179
	ds_read_b128 v[154:157], v179 offset:1024
	ds_read_b128 v[172:175], v179 offset:2048
	ds_read_b128 v[180:183], v179 offset:3072
	v_lshl_add_u64 v[212:213], s[20:21], 0, v[170:171]
	s_add_i32 m0, s19, 0xc000
	ds_read_b128 v[184:187], v178
	ds_read_b128 v[188:191], v178 offset:1024
	ds_read_b128 v[192:195], v178 offset:2048
	ds_read_b128 v[196:199], v178 offset:3072
	ds_read_b128 v[200:203], v178 offset:4096
	ds_read_b128 v[204:207], v178 offset:5120
	ds_read_b128 v[208:211], v178 offset:6144
	ds_read_b128 v[222:225], v178 offset:7168
	s_setprio 2
	global_load_lds_dwordx4 v[212:213], off
	v_lshl_add_u64 v[212:213], s[20:21], 0, v[168:169]
	s_add_i32 m0, s19, 0xe000
	s_nop 0
	global_load_lds_dwordx4 v[212:213], off
	s_setprio 0
	s_cmp_lg_u32 s98, 0
	s_cbranch_scc1 .Lrelax_g5_w1
	s_waitcnt vmcnt(8)
.Lback_g5_w1:
	s_waitcnt lgkmcnt(0)
	s_barrier
	s_setprio 1
	s_waitcnt lgkmcnt(0)
	v_mfma_f32_16x16x32_bf16 v[142:145], v[122:125], v[184:187], v[142:145]
	v_mfma_f32_16x16x32_bf16 v[138:141], v[130:133], v[184:187], v[138:141]
	v_mfma_f32_16x16x32_bf16 v[118:121], v[122:125], v[192:195], v[118:121]
	v_mfma_f32_16x16x32_bf16 v[106:109], v[130:133], v[192:195], v[106:109]
	v_mfma_f32_16x16x32_bf16 v[98:101], v[122:125], v[200:203], v[98:101]
	v_mfma_f32_16x16x32_bf16 v[90:93], v[130:133], v[200:203], v[90:93]
	v_mfma_f32_16x16x32_bf16 v[86:89], v[122:125], v[208:211], v[86:89]
	v_mfma_f32_16x16x32_bf16 v[74:77], v[130:133], v[208:211], v[74:77]
	v_mfma_f32_16x16x32_bf16 v[142:145], v[126:129], v[188:191], v[142:145]
	v_mfma_f32_16x16x32_bf16 v[138:141], v[134:137], v[188:191], v[138:141]
	v_mfma_f32_16x16x32_bf16 v[118:121], v[126:129], v[196:199], v[118:121]
	v_mfma_f32_16x16x32_bf16 v[106:109], v[134:137], v[196:199], v[106:109]
	v_mfma_f32_16x16x32_bf16 v[98:101], v[126:129], v[204:207], v[98:101]
	v_mfma_f32_16x16x32_bf16 v[90:93], v[134:137], v[204:207], v[90:93]
	v_mfma_f32_16x16x32_bf16 v[86:89], v[126:129], v[222:225], v[86:89]
	v_mfma_f32_16x16x32_bf16 v[74:77], v[134:137], v[222:225], v[74:77]
	s_setprio 0
	s_setprio 1
	v_mfma_f32_16x16x32_bf16 v[114:117], v[146:149], v[184:187], v[114:117]
	v_mfma_f32_16x16x32_bf16 v[110:113], v[172:175], v[184:187], v[110:113]
	v_mfma_f32_16x16x32_bf16 v[102:105], v[146:149], v[192:195], v[102:105]
	v_mfma_f32_16x16x32_bf16 v[94:97], v[172:175], v[192:195], v[94:97]
	v_mfma_f32_16x16x32_bf16 v[82:85], v[146:149], v[200:203], v[82:85]
	v_mfma_f32_16x16x32_bf16 v[78:81], v[172:175], v[200:203], v[78:81]
	v_mfma_f32_16x16x32_bf16 v[70:73], v[146:149], v[208:211], v[70:73]
	v_mfma_f32_16x16x32_bf16 v[66:69], v[172:175], v[208:211], v[66:69]
	v_mfma_f32_16x16x32_bf16 v[114:117], v[154:157], v[188:191], v[114:117]
	v_mfma_f32_16x16x32_bf16 v[110:113], v[180:183], v[188:191], v[110:113]
	v_mfma_f32_16x16x32_bf16 v[102:105], v[154:157], v[196:199], v[102:105]
	v_mfma_f32_16x16x32_bf16 v[94:97], v[180:183], v[196:199], v[94:97]
	v_mfma_f32_16x16x32_bf16 v[82:85], v[154:157], v[204:207], v[82:85]
	v_mfma_f32_16x16x32_bf16 v[78:81], v[180:183], v[204:207], v[78:81]
	v_mfma_f32_16x16x32_bf16 v[70:73], v[154:157], v[222:225], v[70:73]
	v_mfma_f32_16x16x32_bf16 v[66:69], v[180:183], v[222:225], v[66:69]
	s_setprio 0
	s_barrier
	s_add_i32 s57, s57, s31
	v_lshl_add_u64 v[212:213], s[22:23], 0, v[0:1]
	s_mov_b32 m0, s57
	ds_read_b128 v[184:187], v178 offset:16384
	ds_read_b128 v[188:191], v178 offset:17408
	ds_read_b128 v[192:195], v178 offset:18432
	ds_read_b128 v[196:199], v178 offset:19456
	ds_read_b128 v[200:203], v178 offset:20480
	ds_read_b128 v[204:207], v178 offset:21504
	ds_read_b128 v[208:211], v178 offset:22528
	ds_read_b128 v[222:225], v178 offset:23552
	s_setprio 2
	global_load_lds_dwordx4 v[212:213], off
	s_add_i32 m0, s57, 0x2000
	s_add_u32 s58, s22, 0x100000
	v_lshl_add_u64 v[226:227], s[22:23], 0, v[166:167]
	s_addc_u32 s59, s23, 0
	s_add_i32 s57, s60, s31
	global_load_lds_dwordx4 v[226:227], off
	v_lshl_add_u64 v[228:229], s[58:59], 0, v[0:1]
	s_mov_b32 m0, s57
	v_lshl_add_u64 v[230:231], s[24:25], 0, v[164:165]
	global_load_lds_dwordx4 v[228:229], off
	v_lshl_add_u64 v[228:229], s[58:59], 0, v[166:167]
	s_add_i32 m0, s57, 0x2000
	s_nop 0
	global_load_lds_dwordx4 v[228:229], off
	v_lshl_add_u64 v[228:229], s[24:25], 0, v[162:163]
	s_mov_b32 m0, s19
	s_nop 0
	global_load_lds_dwordx4 v[228:229], off
	s_mov_b32 m0, s37
	s_nop 0
	global_load_lds_dwordx4 v[230:231], off
	s_setprio 0
	s_cmp_lg_u32 s98, 0
	s_cbranch_scc1 .Lrelax_g5_w2
	s_waitcnt vmcnt(8)
.Lback_g5_w2:
	s_waitcnt lgkmcnt(0)
	s_barrier
	s_setprio 1
	s_waitcnt lgkmcnt(0)
	v_mfma_f32_16x16x32_bf16 v[62:65], v[122:125], v[184:187], v[62:65]
	v_mfma_f32_16x16x32_bf16 v[58:61], v[130:133], v[184:187], v[58:61]
	v_mfma_f32_16x16x32_bf16 v[54:57], v[122:125], v[192:195], v[54:57]
	v_mfma_f32_16x16x32_bf16 v[42:45], v[130:133], v[192:195], v[42:45]
	v_mfma_f32_16x16x32_bf16 v[34:37], v[122:125], v[200:203], v[34:37]
	v_mfma_f32_16x16x32_bf16 v[26:29], v[130:133], v[200:203], v[26:29]
	v_mfma_f32_16x16x32_bf16 v[22:25], v[122:125], v[208:211], v[22:25]
	v_mfma_f32_16x16x32_bf16 v[10:13], v[130:133], v[208:211], v[10:13]
	v_mfma_f32_16x16x32_bf16 v[62:65], v[126:129], v[188:191], v[62:65]
	v_mfma_f32_16x16x32_bf16 v[58:61], v[134:137], v[188:191], v[58:61]
	v_mfma_f32_16x16x32_bf16 v[54:57], v[126:129], v[196:199], v[54:57]
	v_mfma_f32_16x16x32_bf16 v[42:45], v[134:137], v[196:199], v[42:45]
	v_mfma_f32_16x16x32_bf16 v[34:37], v[126:129], v[204:207], v[34:37]
	v_mfma_f32_16x16x32_bf16 v[26:29], v[134:137], v[204:207], v[26:29]
	v_mfma_f32_16x16x32_bf16 v[22:25], v[126:129], v[222:225], v[22:25]
	v_mfma_f32_16x16x32_bf16 v[10:13], v[134:137], v[222:225], v[10:13]
	s_setprio 0
	s_setprio 1
	v_mfma_f32_16x16x32_bf16 v[50:53], v[146:149], v[184:187], v[50:53]
	v_mfma_f32_16x16x32_bf16 v[46:49], v[172:175], v[184:187], v[46:49]
	v_mfma_f32_16x16x32_bf16 v[38:41], v[146:149], v[192:195], v[38:41]
	v_mfma_f32_16x16x32_bf16 v[30:33], v[172:175], v[192:195], v[30:33]
	v_mfma_f32_16x16x32_bf16 v[18:21], v[146:149], v[200:203], v[18:21]
	v_mfma_f32_16x16x32_bf16 v[14:17], v[172:175], v[200:203], v[14:17]
	v_mfma_f32_16x16x32_bf16 v[6:9], v[146:149], v[208:211], v[6:9]
	v_mfma_f32_16x16x32_bf16 v[2:5], v[172:175], v[208:211], v[2:5]
	v_mfma_f32_16x16x32_bf16 v[50:53], v[154:157], v[188:191], v[50:53]
	v_mfma_f32_16x16x32_bf16 v[46:49], v[180:183], v[188:191], v[46:49]
	v_mfma_f32_16x16x32_bf16 v[38:41], v[154:157], v[196:199], v[38:41]
	v_mfma_f32_16x16x32_bf16 v[30:33], v[180:183], v[196:199], v[30:33]
	v_mfma_f32_16x16x32_bf16 v[18:21], v[154:157], v[204:207], v[18:21]
	v_mfma_f32_16x16x32_bf16 v[14:17], v[180:183], v[204:207], v[14:17]
	v_mfma_f32_16x16x32_bf16 v[6:9], v[154:157], v[222:225], v[6:9]
	v_mfma_f32_16x16x32_bf16 v[2:5], v[180:183], v[222:225], v[2:5]
	s_setprio 0
	s_barrier
	s_add_i32 s57, 0, 0x18000
	s_add_i32 s58, 0, 0x1c000
	v_add_u32_e32 v134, s57, v176
	v_add_u32_e32 v179, s58, v176
	ds_read_b128 v[122:125], v134
	ds_read_b128 v[126:129], v134 offset:1024
	ds_read_b128 v[130:133], v134 offset:2048
	ds_read_b128 v[134:137], v134 offset:3072
	ds_read_b128 v[146:149], v179
	ds_read_b128 v[154:157], v179 offset:1024
	ds_read_b128 v[172:175], v179 offset:2048
	ds_read_b128 v[180:183], v179 offset:3072
	s_add_u32 s24, s24, 0x100000
	s_addc_u32 s25, s25, 0
	s_mov_b32 m0, s38
	v_lshl_add_u64 v[232:233], s[24:25], 0, v[162:163]
	ds_read_b128 v[184:187], v178 offset:32768
	ds_read_b128 v[188:191], v178 offset:33792
	ds_read_b128 v[192:195], v178 offset:34816
	ds_read_b128 v[196:199], v178 offset:35840
	ds_read_b128 v[200:203], v178 offset:36864
	ds_read_b128 v[204:207], v178 offset:37888
	ds_read_b128 v[208:211], v178 offset:38912
	ds_read_b128 v[222:225], v178 offset:39936
	s_setprio 2
	global_load_lds_dwordx4 v[232:233], off
	v_lshl_add_u64 v[232:233], s[24:25], 0, v[164:165]
	s_mov_b32 m0, s39
	s_nop 0
	global_load_lds_dwordx4 v[232:233], off
	s_setprio 0
	s_waitcnt vmcnt(8)
	s_waitcnt lgkmcnt(0)
	s_barrier
	s_setprio 1
	s_waitcnt lgkmcnt(0)
	v_mfma_f32_16x16x32_bf16 v[142:145], v[122:125], v[184:187], v[142:145]
	v_mfma_f32_16x16x32_bf16 v[138:141], v[130:133], v[184:187], v[138:141]
	v_mfma_f32_16x16x32_bf16 v[118:121], v[122:125], v[192:195], v[118:121]
	v_mfma_f32_16x16x32_bf16 v[106:109], v[130:133], v[192:195], v[106:109]
	v_mfma_f32_16x16x32_bf16 v[98:101], v[122:125], v[200:203], v[98:101]
	v_mfma_f32_16x16x32_bf16 v[90:93], v[130:133], v[200:203], v[90:93]
	v_mfma_f32_16x16x32_bf16 v[86:89], v[122:125], v[208:211], v[86:89]
	v_mfma_f32_16x16x32_bf16 v[74:77], v[130:133], v[208:211], v[74:77]
	v_mfma_f32_16x16x32_bf16 v[142:145], v[126:129], v[188:191], v[142:145]
	v_mfma_f32_16x16x32_bf16 v[138:141], v[134:137], v[188:191], v[138:141]
	v_mfma_f32_16x16x32_bf16 v[118:121], v[126:129], v[196:199], v[118:121]
	v_mfma_f32_16x16x32_bf16 v[106:109], v[134:137], v[196:199], v[106:109]
	v_mfma_f32_16x16x32_bf16 v[98:101], v[126:129], v[204:207], v[98:101]
	v_mfma_f32_16x16x32_bf16 v[90:93], v[134:137], v[204:207], v[90:93]
	v_mfma_f32_16x16x32_bf16 v[86:89], v[126:129], v[222:225], v[86:89]
	v_mfma_f32_16x16x32_bf16 v[74:77], v[134:137], v[222:225], v[74:77]
	s_setprio 0
	s_setprio 1
	v_mfma_f32_16x16x32_bf16 v[114:117], v[146:149], v[184:187], v[114:117]
	v_mfma_f32_16x16x32_bf16 v[110:113], v[172:175], v[184:187], v[110:113]
	v_mfma_f32_16x16x32_bf16 v[102:105], v[146:149], v[192:195], v[102:105]
	v_mfma_f32_16x16x32_bf16 v[94:97], v[172:175], v[192:195], v[94:97]
	v_mfma_f32_16x16x32_bf16 v[82:85], v[146:149], v[200:203], v[82:85]
	v_mfma_f32_16x16x32_bf16 v[78:81], v[172:175], v[200:203], v[78:81]
	v_mfma_f32_16x16x32_bf16 v[70:73], v[146:149], v[208:211], v[70:73]
	v_mfma_f32_16x16x32_bf16 v[66:69], v[172:175], v[208:211], v[66:69]
	v_mfma_f32_16x16x32_bf16 v[114:117], v[154:157], v[188:191], v[114:117]
	v_mfma_f32_16x16x32_bf16 v[110:113], v[180:183], v[188:191], v[110:113]
	v_mfma_f32_16x16x32_bf16 v[102:105], v[154:157], v[196:199], v[102:105]
	v_mfma_f32_16x16x32_bf16 v[94:97], v[180:183], v[196:199], v[94:97]
	v_mfma_f32_16x16x32_bf16 v[82:85], v[154:157], v[204:207], v[82:85]
	v_mfma_f32_16x16x32_bf16 v[78:81], v[180:183], v[204:207], v[78:81]
	v_mfma_f32_16x16x32_bf16 v[70:73], v[154:157], v[222:225], v[70:73]
	v_mfma_f32_16x16x32_bf16 v[66:69], v[180:183], v[222:225], v[66:69]
	s_setprio 0
	s_barrier
	s_add_i32 s24, s57, s31
	v_lshl_add_u64 v[212:213], v[212:213], 0, s[96:97]
	s_mov_b32 m0, s24
	ds_read_b128 v[184:187], v178 offset:49152
	ds_read_b128 v[188:191], v178 offset:50176
	ds_read_b128 v[192:195], v178 offset:51200
	ds_read_b128 v[196:199], v178 offset:52224
	ds_read_b128 v[200:203], v178 offset:53248
	ds_read_b128 v[204:207], v178 offset:54272
	ds_read_b128 v[208:211], v178 offset:55296
	ds_read_b128 v[222:225], v178 offset:56320
	s_setprio 2
	global_load_lds_dwordx4 v[212:213], off
	s_add_i32 m0, s24, 0x2000
	s_add_u32 s22, s22, 0x100080
	v_lshl_add_u64 v[212:213], v[226:227], 0, s[96:97]
	s_addc_u32 s23, s23, 0
	s_add_i32 s24, s58, s31
	global_load_lds_dwordx4 v[212:213], off
	v_lshl_add_u64 v[212:213], s[22:23], 0, v[0:1]
	s_mov_b32 m0, s24
	s_nop 0
	global_load_lds_dwordx4 v[212:213], off
	v_lshl_add_u64 v[212:213], s[22:23], 0, v[166:167]
	s_add_i32 m0, s24, 0x2000
	s_nop 0
	global_load_lds_dwordx4 v[212:213], off
	v_lshl_add_u64 v[212:213], v[228:229], 0, s[96:97]
	s_mov_b32 m0, s42
	s_nop 0
	global_load_lds_dwordx4 v[212:213], off
	v_lshl_add_u64 v[212:213], v[230:231], 0, s[96:97]
	s_mov_b32 m0, s43
	s_nop 0
	global_load_lds_dwordx4 v[212:213], off
	s_setprio 0
	s_waitcnt vmcnt(8)
	s_waitcnt lgkmcnt(0)
	s_barrier
	s_setprio 1
	s_waitcnt lgkmcnt(0)
	v_mfma_f32_16x16x32_bf16 v[62:65], v[122:125], v[184:187], v[62:65]
	v_mfma_f32_16x16x32_bf16 v[58:61], v[130:133], v[184:187], v[58:61]
	v_mfma_f32_16x16x32_bf16 v[54:57], v[122:125], v[192:195], v[54:57]
	v_mfma_f32_16x16x32_bf16 v[42:45], v[130:133], v[192:195], v[42:45]
	v_mfma_f32_16x16x32_bf16 v[34:37], v[122:125], v[200:203], v[34:37]
	v_mfma_f32_16x16x32_bf16 v[26:29], v[130:133], v[200:203], v[26:29]
	v_mfma_f32_16x16x32_bf16 v[22:25], v[122:125], v[208:211], v[22:25]
	v_mfma_f32_16x16x32_bf16 v[10:13], v[130:133], v[208:211], v[10:13]
	v_mfma_f32_16x16x32_bf16 v[62:65], v[126:129], v[188:191], v[62:65]
	v_mfma_f32_16x16x32_bf16 v[58:61], v[134:137], v[188:191], v[58:61]
	v_mfma_f32_16x16x32_bf16 v[54:57], v[126:129], v[196:199], v[54:57]
	v_mfma_f32_16x16x32_bf16 v[42:45], v[134:137], v[196:199], v[42:45]
	v_mfma_f32_16x16x32_bf16 v[34:37], v[126:129], v[204:207], v[34:37]
	v_mfma_f32_16x16x32_bf16 v[26:29], v[134:137], v[204:207], v[26:29]
	v_mfma_f32_16x16x32_bf16 v[22:25], v[126:129], v[222:225], v[22:25]
	v_mfma_f32_16x16x32_bf16 v[10:13], v[134:137], v[222:225], v[10:13]
	s_setprio 0
	s_setprio 1
	v_mfma_f32_16x16x32_bf16 v[50:53], v[146:149], v[184:187], v[50:53]
	v_mfma_f32_16x16x32_bf16 v[46:49], v[172:175], v[184:187], v[46:49]
	v_mfma_f32_16x16x32_bf16 v[38:41], v[146:149], v[192:195], v[38:41]
	v_mfma_f32_16x16x32_bf16 v[30:33], v[172:175], v[192:195], v[30:33]
	v_mfma_f32_16x16x32_bf16 v[18:21], v[146:149], v[200:203], v[18:21]
	v_mfma_f32_16x16x32_bf16 v[14:17], v[172:175], v[200:203], v[14:17]
	v_mfma_f32_16x16x32_bf16 v[6:9], v[146:149], v[208:211], v[6:9]
	v_mfma_f32_16x16x32_bf16 v[2:5], v[172:175], v[208:211], v[2:5]
	v_mfma_f32_16x16x32_bf16 v[50:53], v[154:157], v[188:191], v[50:53]
	v_mfma_f32_16x16x32_bf16 v[46:49], v[180:183], v[188:191], v[46:49]
	v_mfma_f32_16x16x32_bf16 v[38:41], v[154:157], v[196:199], v[38:41]
	v_mfma_f32_16x16x32_bf16 v[30:33], v[180:183], v[196:199], v[30:33]
	v_mfma_f32_16x16x32_bf16 v[18:21], v[154:157], v[204:207], v[18:21]
	v_mfma_f32_16x16x32_bf16 v[14:17], v[180:183], v[204:207], v[14:17]
	v_mfma_f32_16x16x32_bf16 v[6:9], v[154:157], v[222:225], v[6:9]
	v_mfma_f32_16x16x32_bf16 v[2:5], v[180:183], v[222:225], v[2:5]
	s_setprio 0
	s_barrier
	s_add_i32 s56, s56, 2
	s_add_u32 s49, s49, 0x100
	s_addc_u32 s55, s55, 0
	s_add_u32 s20, s20, 0x100
	s_addc_u32 s21, s21, 0
	s_cmp_gt_u32 s56, 61
	s_cbranch_scc0 .LBB0_381
	s_and_b64 vcc, exec, s[8:9]
	s_movk_i32 s47, 0xec00
	s_movk_i32 s55, 0xf000
	s_cbranch_vccz .LBB0_384
	s_barrier
